# scan phase: hand-scheduled RWKV/HGRN chunk bodies, loader loads land in place + hand-written staging, batched write-out
# speedup vs baseline: 1.0271x; 1.0271x over previous
; #define LAS __attribute__((address_space(3)))
; #define SC_LOAD(P, chunk) do { _Pragma("unroll") for (int i = 0; i < 8; ++i) if (sk[i] >= 0) P[i] = *(const u32x4*)(sp[i] + (size_t)(chunk) * 16 * sld[i]); } while (0)
; __device__ __forceinline__ void scan_phase(const Params& p, int layer, LAS unsigned char* lds, int tid) {
;     ...
;                 if (c + 1 < NCH) {
;                     if (bi == 0) { LAS float* dstb = INB + IN_F; SC_STAGE(preB, dstb); if (c + 3 < NCH) SC_LOAD(preB, c + 3); }
;                     else { LAS float* dstb = INB; SC_STAGE(preA, dstb); if (c + 3 < NCH) SC_LOAD(preA, c + 3); }
.LBB0_281:
	s_add_i32 s7, s34, 1
	s_and_b32 s24, s7, 1
	s_mul_i32 s10, s24, 0x7800
	s_add_i32 s36, s10, 0
	s_mul_i32 s10, s24, 0xffffa800
	s_add_i32 s33, s36, s10
	s_and_saveexec_b64 s[10:11], s[38:39]
	s_xor_b64 s[18:19], exec, s[10:11]
	s_cbranch_execz .LBB0_420
	s_and_saveexec_b64 s[10:11], s[40:41]
	s_xor_b64 s[20:21], exec, s[10:11]
	s_cbranch_execz .LBB0_385
	s_cmp_lg_u32 s16, 0x1800000
	s_cbranch_scc0 .Lscan_wo
	s_cmp_eq_u32 s24, 0
	s_mov_b64 s[10:11], -1
	s_cbranch_scc1 .LBB0_336
	s_waitcnt vmcnt(15)
	s_cmpk_lt_u32 s7, 3
	s_cbranch_scc1 .Lstg_a7
	s_cmpk_lt_u32 s7, 0xff
	s_cbranch_scc1 .Lstg_a
	s_waitcnt vmcnt(0)
	s_branch .Lstg_a
.Lstg_a7:
	s_waitcnt vmcnt(7)
.Lstg_a:
	s_mov_b64 s[28:29], exec
	v_cmp_eq_u32_e64 s[24:25], 3, v200
	v_cmp_eq_u32_e64 s[26:27], 3, v199
	v_cmp_eq_u32_e64 s[10:11], 4, v201
	v_lshlrev_b32_e32 v76, 16, v48
	v_and_b32_e32 v77, 0xffff0000, v48
	v_lshlrev_b32_e32 v78, 16, v49
	v_and_b32_e32 v79, 0xffff0000, v49
	v_lshlrev_b32_e32 v80, 16, v50
	v_and_b32_e32 v81, 0xffff0000, v50
	v_lshlrev_b32_e32 v82, 16, v51
	v_and_b32_e32 v83, 0xffff0000, v51
	ds_write_b128 v192, v[76:79]
	ds_write_b128 v192, v[80:83] offset:80
	v_lshlrev_b32_e32 v92, 16, v68
	v_and_b32_e32 v93, 0xffff0000, v68
	v_lshlrev_b32_e32 v94, 16, v69
	v_and_b32_e32 v95, 0xffff0000, v69
	v_lshlrev_b32_e32 v96, 16, v70
	v_and_b32_e32 v97, 0xffff0000, v70
	v_lshlrev_b32_e32 v98, 16, v71
	v_and_b32_e32 v99, 0xffff0000, v71
	v_cndmask_b32_e64 v3, 16, 32, s[24:25]
	s_and_b64 exec, s[28:29], s[24:25]
	v_mul_f32_e32 v100, 0xbfb8aa3b, v92
	v_mul_f32_e32 v101, 0xbfb8aa3b, v93
	v_mul_f32_e32 v102, 0xbfb8aa3b, v94
	v_mul_f32_e32 v103, 0xbfb8aa3b, v95
	v_mul_f32_e32 v104, 0xbfb8aa3b, v96
	v_mul_f32_e32 v105, 0xbfb8aa3b, v97
	v_mul_f32_e32 v106, 0xbfb8aa3b, v98
	v_mul_f32_e32 v107, 0xbfb8aa3b, v99
	v_exp_f32_e32 v100, v100
	v_exp_f32_e32 v101, v101
	v_exp_f32_e32 v102, v102
	v_exp_f32_e32 v103, v103
	v_exp_f32_e32 v104, v104
	v_exp_f32_e32 v105, v105
	v_exp_f32_e32 v106, v106
	v_exp_f32_e32 v107, v107
	v_add_f32_e32 v100, 1.0, v100
	v_add_f32_e32 v101, 1.0, v101
	v_add_f32_e32 v102, 1.0, v102
	v_add_f32_e32 v103, 1.0, v103
	v_add_f32_e32 v104, 1.0, v104
	v_add_f32_e32 v105, 1.0, v105
	v_add_f32_e32 v106, 1.0, v106
	v_add_f32_e32 v107, 1.0, v107
	v_rcp_f32_e32 v100, v100
	v_rcp_f32_e32 v101, v101
	v_rcp_f32_e32 v102, v102
	v_rcp_f32_e32 v103, v103
	v_rcp_f32_e32 v104, v104
	v_rcp_f32_e32 v105, v105
	v_rcp_f32_e32 v106, v106
	v_rcp_f32_e32 v107, v107
	v_pk_mul_f32 v[92:93], v[100:101], v[92:93]
	v_pk_mul_f32 v[94:95], v[102:103], v[94:95]
	v_pk_mul_f32 v[96:97], v[104:105], v[96:97]
	v_pk_mul_f32 v[98:99], v[106:107], v[98:99]
	s_mov_b64 exec, s[28:29]
	v_add_u32_e32 v3, v3, v1
	v_lshlrev_b32_e32 v76, 16, v52
	v_and_b32_e32 v77, 0xffff0000, v52
	v_lshlrev_b32_e32 v78, 16, v53
	v_and_b32_e32 v79, 0xffff0000, v53
	v_lshlrev_b32_e32 v80, 16, v54
	v_and_b32_e32 v81, 0xffff0000, v54
	v_lshlrev_b32_e32 v82, 16, v55
	v_and_b32_e32 v83, 0xffff0000, v55
	v_mul_f32_e32 v84, 0x3fb8aa3b, v76
	v_mul_f32_e32 v85, 0x3fb8aa3b, v77
	v_mul_f32_e32 v86, 0x3fb8aa3b, v78
	v_mul_f32_e32 v87, 0x3fb8aa3b, v79
	v_mul_f32_e32 v88, 0x3fb8aa3b, v80
	v_mul_f32_e32 v89, 0x3fb8aa3b, v81
	v_mul_f32_e32 v90, 0x3fb8aa3b, v82
	v_mul_f32_e32 v91, 0x3fb8aa3b, v83
	v_exp_f32_e32 v84, v84
	v_exp_f32_e32 v85, v85
	v_exp_f32_e32 v86, v86
	v_exp_f32_e32 v87, v87
	v_exp_f32_e32 v88, v88
	v_exp_f32_e32 v89, v89
	v_exp_f32_e32 v90, v90
	v_exp_f32_e32 v91, v91
	ds_write_b128 v1, v[92:95]
	ds_write_b128 v3, v[96:99]
	ds_write_b128 v192, v[84:87] offset:16
	ds_write_b128 v192, v[88:91] offset:96
	v_lshlrev_b32_e32 v92, 16, v72
	v_and_b32_e32 v93, 0xffff0000, v72
	v_lshlrev_b32_e32 v94, 16, v73
	v_and_b32_e32 v95, 0xffff0000, v73
	v_lshlrev_b32_e32 v96, 16, v74
	v_and_b32_e32 v97, 0xffff0000, v74
	v_lshlrev_b32_e32 v98, 16, v75
	v_and_b32_e32 v99, 0xffff0000, v75
	v_mul_f32_e32 v100, 0xbfb8aa3b, v92
	v_mul_f32_e32 v101, 0xbfb8aa3b, v93
	v_mul_f32_e32 v102, 0xbfb8aa3b, v94
	v_mul_f32_e32 v103, 0xbfb8aa3b, v95
	v_mul_f32_e32 v104, 0xbfb8aa3b, v96
	v_mul_f32_e32 v105, 0xbfb8aa3b, v97
	v_mul_f32_e32 v106, 0xbfb8aa3b, v98
	v_mul_f32_e32 v107, 0xbfb8aa3b, v99
	v_exp_f32_e32 v100, v100
	v_exp_f32_e32 v101, v101
	v_exp_f32_e32 v102, v102
	v_exp_f32_e32 v103, v103
	v_exp_f32_e32 v104, v104
	v_exp_f32_e32 v105, v105
	v_exp_f32_e32 v106, v106
	v_exp_f32_e32 v107, v107
	v_add_f32_e32 v100, 1.0, v100
	v_add_f32_e32 v101, 1.0, v101
	v_add_f32_e32 v102, 1.0, v102
	v_add_f32_e32 v103, 1.0, v103
	v_add_f32_e32 v104, 1.0, v104
	v_add_f32_e32 v105, 1.0, v105
	v_add_f32_e32 v106, 1.0, v106
	v_add_f32_e32 v107, 1.0, v107
	v_rcp_f32_e32 v100, v100
	v_rcp_f32_e32 v101, v101
	v_rcp_f32_e32 v102, v102
	v_rcp_f32_e32 v103, v103
	v_rcp_f32_e32 v104, v104
	v_rcp_f32_e32 v105, v105
	v_rcp_f32_e32 v106, v106
	v_rcp_f32_e32 v107, v107
	s_and_b64 exec, s[28:29], s[26:27]
	v_pk_mul_f32 v[100:101], v[100:101], v[92:93]
	v_pk_mul_f32 v[102:103], v[102:103], v[94:95]
	v_pk_mul_f32 v[104:105], v[104:105], v[96:97]
	v_pk_mul_f32 v[106:107], v[106:107], v[98:99]
	s_andn2_b64 exec, s[28:29], s[26:27]
	v_pk_fma_f32 v[100:101], v[138:139], v[100:101], v[8:9]
	v_pk_fma_f32 v[102:103], v[140:141], v[102:103], v[10:11]
	v_pk_fma_f32 v[104:105], v[142:143], v[104:105], v[4:5]
	v_pk_fma_f32 v[106:107], v[144:145], v[106:107], v[6:7]
	s_mov_b64 exec, s[28:29]
	v_lshlrev_b32_e32 v76, 16, v56
	v_and_b32_e32 v77, 0xffff0000, v56
	v_lshlrev_b32_e32 v78, 16, v57
	v_and_b32_e32 v79, 0xffff0000, v57
	v_lshlrev_b32_e32 v80, 16, v58
	v_and_b32_e32 v81, 0xffff0000, v58
	v_lshlrev_b32_e32 v82, 16, v59
	v_and_b32_e32 v83, 0xffff0000, v59
	ds_write_b128 v192, v[76:79] offset:32
	ds_write_b128 v192, v[80:83] offset:112
	ds_write_b128 v202, v[100:103]
	ds_write_b128 v202, v[104:107] offset:32
	v_lshlrev_b32_e32 v84, 16, v60
	v_and_b32_e32 v85, 0xffff0000, v60
	v_lshlrev_b32_e32 v86, 16, v61
	v_and_b32_e32 v87, 0xffff0000, v61
	v_lshlrev_b32_e32 v88, 16, v62
	v_and_b32_e32 v89, 0xffff0000, v62
	v_lshlrev_b32_e32 v90, 16, v63
	v_and_b32_e32 v91, 0xffff0000, v63
	ds_write_b128 v192, v[84:87] offset:48
	ds_write_b128 v192, v[88:91] offset:128
	v_lshlrev_b32_e32 v76, 16, v64
	v_and_b32_e32 v77, 0xffff0000, v64
	v_lshlrev_b32_e32 v78, 16, v65
	v_and_b32_e32 v79, 0xffff0000, v65
	v_lshlrev_b32_e32 v80, 16, v66
	v_and_b32_e32 v81, 0xffff0000, v66
	v_lshlrev_b32_e32 v82, 16, v67
	v_and_b32_e32 v83, 0xffff0000, v67
	ds_write_b128 v192, v[76:79] offset:64
	ds_write_b128 v192, v[80:83] offset:144
	s_and_b64 exec, s[28:29], s[52:53]
	s_cbranch_execz .Lstg_a_p7
; #define LAS __attribute__((address_space(3)))
; #define SC_LOAD(P, chunk) do { _Pragma("unroll") for (int i = 0; i < 8; ++i) if (sk[i] >= 0) P[i] = *(const u32x4*)(sp[i] + (size_t)(chunk) * 16 * sld[i]); } while (0)
; __device__ __forceinline__ void scan_phase(const Params& p, int layer, LAS unsigned char* lds, int tid) {
;     ...
;                 if (c + 1 < NCH) {
;                     if (bi == 0) { LAS float* dstb = INB + IN_F; SC_STAGE(preB, dstb); if (c + 3 < NCH) SC_LOAD(preB, c + 3); }
;                     else { LAS float* dstb = INB; SC_STAGE(preA, dstb); if (c + 3 < NCH) SC_LOAD(preA, c + 3); }
	v_lshlrev_b32_e32 v92, 16, v20
	v_and_b32_e32 v93, 0xffff0000, v20
	v_lshlrev_b32_e32 v94, 16, v21
	v_and_b32_e32 v95, 0xffff0000, v21
	v_lshlrev_b32_e32 v96, 16, v22
	v_and_b32_e32 v97, 0xffff0000, v22
	v_lshlrev_b32_e32 v98, 16, v23
	v_and_b32_e32 v99, 0xffff0000, v23
	v_cndmask_b32_e64 v3, 16, 32, s[10:11]
	s_and_b64 exec, exec, s[10:11]
	v_mul_f32_e32 v100, 0xbfb8aa3b, v92
	v_mul_f32_e32 v101, 0xbfb8aa3b, v93
	v_mul_f32_e32 v102, 0xbfb8aa3b, v94
	v_mul_f32_e32 v103, 0xbfb8aa3b, v95
	v_mul_f32_e32 v104, 0xbfb8aa3b, v96
	v_mul_f32_e32 v105, 0xbfb8aa3b, v97
	v_mul_f32_e32 v106, 0xbfb8aa3b, v98
	v_mul_f32_e32 v107, 0xbfb8aa3b, v99
	v_exp_f32_e32 v100, v100
	v_exp_f32_e32 v101, v101
	v_exp_f32_e32 v102, v102
	v_exp_f32_e32 v103, v103
	v_exp_f32_e32 v104, v104
	v_exp_f32_e32 v105, v105
	v_exp_f32_e32 v106, v106
	v_exp_f32_e32 v107, v107
	v_add_f32_e32 v100, 1.0, v100
	v_add_f32_e32 v101, 1.0, v101
	v_add_f32_e32 v102, 1.0, v102
	v_add_f32_e32 v103, 1.0, v103
	v_add_f32_e32 v104, 1.0, v104
	v_add_f32_e32 v105, 1.0, v105
	v_add_f32_e32 v106, 1.0, v106
	v_add_f32_e32 v107, 1.0, v107
	v_rcp_f32_e32 v100, v100
	v_rcp_f32_e32 v101, v101
	v_rcp_f32_e32 v102, v102
	v_rcp_f32_e32 v103, v103
	v_rcp_f32_e32 v104, v104
	v_rcp_f32_e32 v105, v105
	v_rcp_f32_e32 v106, v106
	v_rcp_f32_e32 v107, v107
	v_pk_fma_f32 v[92:93], v[138:139], v[100:101], v[8:9]
	v_pk_fma_f32 v[94:95], v[140:141], v[102:103], v[10:11]
	v_pk_fma_f32 v[96:97], v[142:143], v[104:105], v[4:5]
	v_pk_fma_f32 v[98:99], v[144:145], v[106:107], v[6:7]
	s_and_b64 exec, s[28:29], s[52:53]
	v_add_u32_e32 v3, v3, v203
	ds_write_b128 v203, v[92:95]
	s_nop 0
	ds_write_b128 v3, v[96:99]
.Lstg_a_p7:
	s_mov_b64 exec, s[28:29]
	s_mov_b64 s[24:25], 0
.LBB0_331:
	s_or_b64 exec, exec, s[24:25]
	s_cmpk_lt_u32 s7, 0xfe
	s_cbranch_scc0 .LBB0_335
	v_lshl_add_u64 v[80:81], v[148:149], 0, s[16:17]
	v_add_co_u32_e32 v84, vcc, 0x10248000, v80
	v_lshl_add_u64 v[96:97], v[150:151], 0, s[16:17]
	s_nop 0
	v_addc_co_u32_e32 v85, vcc, 0, v81, vcc
	v_add_co_u32_e32 v88, vcc, 0xfdfe0000, v146
	v_lshl_add_u64 v[100:101], v[152:153], 0, s[16:17]
	s_nop 0
	v_addc_co_u32_e32 v89, vcc, -1, v147, vcc
	v_add_co_u32_e32 v92, vcc, 0xfbfc0000, v146
	global_load_dwordx4 v[48:51], v[146:147], off
	s_nop 0
	v_addc_co_u32_e32 v93, vcc, -1, v147, vcc
	global_load_dwordx4 v[52:55], v[84:85], off
	s_nop 0
	global_load_dwordx4 v[56:59], v[84:85], off offset:512
	s_nop 0
	global_load_dwordx4 v[60:63], v[88:89], off
	s_nop 0
	global_load_dwordx4 v[64:67], v[92:93], off
	global_load_dwordx4 v[68:71], v[96:97], off
	global_load_dwordx4 v[72:75], v[100:101], off
	s_and_saveexec_b64 s[10:11], s[52:53]
	s_cbranch_execz .LBB0_334
	global_load_dwordx4 v[20:23], v[154:155], off

; #define LAS __attribute__((address_space(3)))
; #define SC_LOAD(P, chunk) do { _Pragma("unroll") for (int i = 0; i < 8; ++i) if (sk[i] >= 0) P[i] = *(const u32x4*)(sp[i] + (size_t)(chunk) * 16 * sld[i]); } while (0)
; __device__ __forceinline__ void scan_phase(const Params& p, int layer, LAS unsigned char* lds, int tid) {
;     ...
;                 if (c + 1 < NCH) {
;                     if (bi == 0) { LAS float* dstb = INB + IN_F; SC_STAGE(preB, dstb); if (c + 3 < NCH) SC_LOAD(preB, c + 3); }
;                     else { LAS float* dstb = INB; SC_STAGE(preA, dstb); if (c + 3 < NCH) SC_LOAD(preA, c + 3); }
.LBB0_336:
	s_and_b64 vcc, exec, s[10:11]
	s_cbranch_vccz .LBB0_360
	s_waitcnt vmcnt(15)
	s_cmpk_lt_u32 s7, 3
	s_cbranch_scc1 .Lstg_b7
	s_cmpk_lt_u32 s7, 0xff
	s_cbranch_scc1 .Lstg_b
	s_waitcnt vmcnt(0)
	s_branch .Lstg_b

.Lstg_b:
	s_mov_b64 s[28:29], exec
	v_cmp_eq_u32_e64 s[24:25], 3, v200
	v_cmp_eq_u32_e64 s[26:27], 3, v199
	v_cmp_eq_u32_e64 s[10:11], 4, v201
	v_lshlrev_b32_e32 v76, 16, v16
	v_and_b32_e32 v77, 0xffff0000, v16
	v_lshlrev_b32_e32 v78, 16, v17
	v_and_b32_e32 v79, 0xffff0000, v17
	v_lshlrev_b32_e32 v80, 16, v18
	v_and_b32_e32 v81, 0xffff0000, v18
	v_lshlrev_b32_e32 v82, 16, v19
	v_and_b32_e32 v83, 0xffff0000, v19
	ds_write_b128 v192, v[76:79] offset:30720
	ds_write_b128 v192, v[80:83] offset:30800
	v_lshlrev_b32_e32 v92, 16, v40
	v_and_b32_e32 v93, 0xffff0000, v40
	v_lshlrev_b32_e32 v94, 16, v41
	v_and_b32_e32 v95, 0xffff0000, v41
	v_lshlrev_b32_e32 v96, 16, v42
	v_and_b32_e32 v97, 0xffff0000, v42
	v_lshlrev_b32_e32 v98, 16, v43
	v_and_b32_e32 v99, 0xffff0000, v43
	v_cndmask_b32_e64 v3, 16, 32, s[24:25]
	s_and_b64 exec, s[28:29], s[24:25]
	v_mul_f32_e32 v100, 0xbfb8aa3b, v92
	v_mul_f32_e32 v101, 0xbfb8aa3b, v93
	v_mul_f32_e32 v102, 0xbfb8aa3b, v94
	v_mul_f32_e32 v103, 0xbfb8aa3b, v95
	v_mul_f32_e32 v104, 0xbfb8aa3b, v96
	v_mul_f32_e32 v105, 0xbfb8aa3b, v97
	v_mul_f32_e32 v106, 0xbfb8aa3b, v98
	v_mul_f32_e32 v107, 0xbfb8aa3b, v99
	v_exp_f32_e32 v100, v100
	v_exp_f32_e32 v101, v101
	v_exp_f32_e32 v102, v102
	v_exp_f32_e32 v103, v103
	v_exp_f32_e32 v104, v104
	v_exp_f32_e32 v105, v105
	v_exp_f32_e32 v106, v106
	v_exp_f32_e32 v107, v107
	v_add_f32_e32 v100, 1.0, v100
	v_add_f32_e32 v101, 1.0, v101
	v_add_f32_e32 v102, 1.0, v102
	v_add_f32_e32 v103, 1.0, v103
	v_add_f32_e32 v104, 1.0, v104
	v_add_f32_e32 v105, 1.0, v105
	v_add_f32_e32 v106, 1.0, v106
	v_add_f32_e32 v107, 1.0, v107
	v_rcp_f32_e32 v100, v100
	v_rcp_f32_e32 v101, v101
	v_rcp_f32_e32 v102, v102
	v_rcp_f32_e32 v103, v103
	v_rcp_f32_e32 v104, v104
	v_rcp_f32_e32 v105, v105
	v_rcp_f32_e32 v106, v106
	v_rcp_f32_e32 v107, v107
	v_pk_mul_f32 v[92:93], v[100:101], v[92:93]
	v_pk_mul_f32 v[94:95], v[102:103], v[94:95]
	v_pk_mul_f32 v[96:97], v[104:105], v[96:97]
	v_pk_mul_f32 v[98:99], v[106:107], v[98:99]
	s_mov_b64 exec, s[28:29]
	v_add_u32_e32 v3, v3, v1
	v_lshlrev_b32_e32 v76, 16, v24
	v_and_b32_e32 v77, 0xffff0000, v24
	v_lshlrev_b32_e32 v78, 16, v25
	v_and_b32_e32 v79, 0xffff0000, v25
	v_lshlrev_b32_e32 v80, 16, v26
	v_and_b32_e32 v81, 0xffff0000, v26
	v_lshlrev_b32_e32 v82, 16, v27
	v_and_b32_e32 v83, 0xffff0000, v27
	v_mul_f32_e32 v84, 0x3fb8aa3b, v76
	v_mul_f32_e32 v85, 0x3fb8aa3b, v77
	v_mul_f32_e32 v86, 0x3fb8aa3b, v78
	v_mul_f32_e32 v87, 0x3fb8aa3b, v79
	v_mul_f32_e32 v88, 0x3fb8aa3b, v80
	v_mul_f32_e32 v89, 0x3fb8aa3b, v81
	v_mul_f32_e32 v90, 0x3fb8aa3b, v82
	v_mul_f32_e32 v91, 0x3fb8aa3b, v83
	v_exp_f32_e32 v84, v84
	v_exp_f32_e32 v85, v85
	v_exp_f32_e32 v86, v86
	v_exp_f32_e32 v87, v87
	v_exp_f32_e32 v88, v88
	v_exp_f32_e32 v89, v89
	v_exp_f32_e32 v90, v90
	v_exp_f32_e32 v91, v91
	ds_write_b128 v1, v[92:95] offset:30720
	ds_write_b128 v3, v[96:99] offset:30720
	ds_write_b128 v192, v[84:87] offset:30736
	ds_write_b128 v192, v[88:91] offset:30816
	v_lshlrev_b32_e32 v92, 16, v44
	v_and_b32_e32 v93, 0xffff0000, v44
	v_lshlrev_b32_e32 v94, 16, v45
	v_and_b32_e32 v95, 0xffff0000, v45
	v_lshlrev_b32_e32 v96, 16, v46
	v_and_b32_e32 v97, 0xffff0000, v46
	v_lshlrev_b32_e32 v98, 16, v47
	v_and_b32_e32 v99, 0xffff0000, v47
	v_mul_f32_e32 v100, 0xbfb8aa3b, v92
	v_mul_f32_e32 v101, 0xbfb8aa3b, v93
	v_mul_f32_e32 v102, 0xbfb8aa3b, v94
	v_mul_f32_e32 v103, 0xbfb8aa3b, v95
	v_mul_f32_e32 v104, 0xbfb8aa3b, v96
	v_mul_f32_e32 v105, 0xbfb8aa3b, v97
	v_mul_f32_e32 v106, 0xbfb8aa3b, v98
	v_mul_f32_e32 v107, 0xbfb8aa3b, v99
	v_exp_f32_e32 v100, v100
	v_exp_f32_e32 v101, v101
	v_exp_f32_e32 v102, v102
	v_exp_f32_e32 v103, v103
	v_exp_f32_e32 v104, v104
	v_exp_f32_e32 v105, v105
	v_exp_f32_e32 v106, v106
	v_exp_f32_e32 v107, v107
	v_add_f32_e32 v100, 1.0, v100
	v_add_f32_e32 v101, 1.0, v101
	v_add_f32_e32 v102, 1.0, v102
	v_add_f32_e32 v103, 1.0, v103
	v_add_f32_e32 v104, 1.0, v104
	v_add_f32_e32 v105, 1.0, v105
	v_add_f32_e32 v106, 1.0, v106
	v_add_f32_e32 v107, 1.0, v107
	v_rcp_f32_e32 v100, v100
	v_rcp_f32_e32 v101, v101
	v_rcp_f32_e32 v102, v102
	v_rcp_f32_e32 v103, v103
	v_rcp_f32_e32 v104, v104
	v_rcp_f32_e32 v105, v105
	v_rcp_f32_e32 v106, v106
	v_rcp_f32_e32 v107, v107
	s_and_b64 exec, s[28:29], s[26:27]
	v_pk_mul_f32 v[100:101], v[100:101], v[92:93]
	v_pk_mul_f32 v[102:103], v[102:103], v[94:95]
	v_pk_mul_f32 v[104:105], v[104:105], v[96:97]
	v_pk_mul_f32 v[106:107], v[106:107], v[98:99]
	s_andn2_b64 exec, s[28:29], s[26:27]
	v_pk_fma_f32 v[100:101], v[138:139], v[100:101], v[8:9]
	v_pk_fma_f32 v[102:103], v[140:141], v[102:103], v[10:11]
	v_pk_fma_f32 v[104:105], v[142:143], v[104:105], v[4:5]
	v_pk_fma_f32 v[106:107], v[144:145], v[106:107], v[6:7]
	s_mov_b64 exec, s[28:29]
	v_lshlrev_b32_e32 v76, 16, v28
	v_and_b32_e32 v77, 0xffff0000, v28
	v_lshlrev_b32_e32 v78, 16, v29
	v_and_b32_e32 v79, 0xffff0000, v29
	v_lshlrev_b32_e32 v80, 16, v30
	v_and_b32_e32 v81, 0xffff0000, v30
	v_lshlrev_b32_e32 v82, 16, v31
	v_and_b32_e32 v83, 0xffff0000, v31
	ds_write_b128 v192, v[76:79] offset:30752
	ds_write_b128 v192, v[80:83] offset:30832
	ds_write_b128 v202, v[100:103] offset:30720
	ds_write_b128 v202, v[104:107] offset:30752
	v_lshlrev_b32_e32 v84, 16, v32
	v_and_b32_e32 v85, 0xffff0000, v32
	v_lshlrev_b32_e32 v86, 16, v33
	v_and_b32_e32 v87, 0xffff0000, v33
	v_lshlrev_b32_e32 v88, 16, v34
	v_and_b32_e32 v89, 0xffff0000, v34
	v_lshlrev_b32_e32 v90, 16, v35
	v_and_b32_e32 v91, 0xffff0000, v35
	ds_write_b128 v192, v[84:87] offset:30768
	ds_write_b128 v192, v[88:91] offset:30848
	v_lshlrev_b32_e32 v76, 16, v36
	v_and_b32_e32 v77, 0xffff0000, v36
	v_lshlrev_b32_e32 v78, 16, v37
	v_and_b32_e32 v79, 0xffff0000, v37
	v_lshlrev_b32_e32 v80, 16, v38
	v_and_b32_e32 v81, 0xffff0000, v38
	v_lshlrev_b32_e32 v82, 16, v39
	v_and_b32_e32 v83, 0xffff0000, v39
	ds_write_b128 v192, v[76:79] offset:30784
	ds_write_b128 v192, v[80:83] offset:30864
	s_and_b64 exec, s[28:29], s[52:53]
	s_cbranch_execz .Lstg_b_p7
; #define LAS __attribute__((address_space(3)))
; #define SC_LOAD(P, chunk) do { _Pragma("unroll") for (int i = 0; i < 8; ++i) if (sk[i] >= 0) P[i] = *(const u32x4*)(sp[i] + (size_t)(chunk) * 16 * sld[i]); } while (0)
; __device__ __forceinline__ void scan_phase(const Params& p, int layer, LAS unsigned char* lds, int tid) {
;     ...
;                     if (bi == 0) { LAS float* dstb = INB + IN_F; SC_STAGE(preB, dstb); if (c + 3 < NCH) SC_LOAD(preB, c + 3); }
;                     else { LAS float* dstb = INB; SC_STAGE(preA, dstb); if (c + 3 < NCH) SC_LOAD(preA, c + 3); }
	v_lshlrev_b32_e32 v92, 16, v12
	v_and_b32_e32 v93, 0xffff0000, v12
	v_lshlrev_b32_e32 v94, 16, v13
	v_and_b32_e32 v95, 0xffff0000, v13
	v_lshlrev_b32_e32 v96, 16, v14
	v_and_b32_e32 v97, 0xffff0000, v14
	v_lshlrev_b32_e32 v98, 16, v15
	v_and_b32_e32 v99, 0xffff0000, v15
	v_cndmask_b32_e64 v3, 16, 32, s[10:11]
	s_and_b64 exec, exec, s[10:11]
	v_mul_f32_e32 v100, 0xbfb8aa3b, v92
	v_mul_f32_e32 v101, 0xbfb8aa3b, v93
	v_mul_f32_e32 v102, 0xbfb8aa3b, v94
	v_mul_f32_e32 v103, 0xbfb8aa3b, v95
	v_mul_f32_e32 v104, 0xbfb8aa3b, v96
	v_mul_f32_e32 v105, 0xbfb8aa3b, v97
	v_mul_f32_e32 v106, 0xbfb8aa3b, v98
	v_mul_f32_e32 v107, 0xbfb8aa3b, v99
	v_exp_f32_e32 v100, v100
	v_exp_f32_e32 v101, v101
	v_exp_f32_e32 v102, v102
	v_exp_f32_e32 v103, v103
	v_exp_f32_e32 v104, v104
	v_exp_f32_e32 v105, v105
	v_exp_f32_e32 v106, v106
	v_exp_f32_e32 v107, v107
	v_add_f32_e32 v100, 1.0, v100
	v_add_f32_e32 v101, 1.0, v101
	v_add_f32_e32 v102, 1.0, v102
	v_add_f32_e32 v103, 1.0, v103
	v_add_f32_e32 v104, 1.0, v104
	v_add_f32_e32 v105, 1.0, v105
	v_add_f32_e32 v106, 1.0, v106
	v_add_f32_e32 v107, 1.0, v107
	v_rcp_f32_e32 v100, v100
	v_rcp_f32_e32 v101, v101
	v_rcp_f32_e32 v102, v102
	v_rcp_f32_e32 v103, v103
	v_rcp_f32_e32 v104, v104
	v_rcp_f32_e32 v105, v105
	v_rcp_f32_e32 v106, v106
	v_rcp_f32_e32 v107, v107
	v_pk_fma_f32 v[92:93], v[138:139], v[100:101], v[8:9]
	v_pk_fma_f32 v[94:95], v[140:141], v[102:103], v[10:11]
	v_pk_fma_f32 v[96:97], v[142:143], v[104:105], v[4:5]
	v_pk_fma_f32 v[98:99], v[144:145], v[106:107], v[6:7]
	s_and_b64 exec, s[28:29], s[52:53]
	v_add_u32_e32 v3, v3, v203
	ds_write_b128 v203, v[92:95] offset:30720
	s_nop 0
	ds_write_b128 v3, v[96:99] offset:30720
.Lstg_b_p7:
	s_mov_b64 exec, s[28:29]
	s_mov_b64 s[24:25], 0
	s_branch .LBB0_382
.LBB0_360:
	s_branch .Lscan_wo

; #define LAS __attribute__((address_space(3)))
; __device__ __forceinline__ unsigned f2bf(float f) { unsigned u = __float_as_uint(f); return (u + 0x7fffu + ((u >> 16) & 1u)) >> 16; }
; __device__ __forceinline__ void scan_phase(const Params& p, int layer, LAS unsigned char* lds, int tid) {
;     ...
;                 if (c > 0) {
; #pragma unroll
;                     for (int i = 0; i < 2; ++i) { const int oi = lt + 128 * i;
;                         const LAS float* po = OUTB + (bi ^ 1) * OUT_F + (oi >> 4) * 64 + (oi & 15);
;                         const size_t mo = (mb + (size_t)(c - 1) * 16 + (oi >> 4)) * 256 + h * 64 + rq * 16 + (oi & 15);
;                         YA[mo] = (bf16)f2bf((po[0] + po[16]) + (po[32] + po[48]));
;                         YD[mo] = (bf16)f2bf((po[O_HO] + po[O_HO + 16]) + (po[O_HO + 32] + po[O_HO + 48])); }
;                 }
.Lscan_wo:
	s_cmp_eq_u32 s16, 0
	s_cbranch_scc1 .LBB0_385
	s_and_b32 s10, s7, 1
	s_lshl_b32 s10, s10, 13
	s_xor_b32 s10, s10, 0x2000
	s_add_i32 s10, s10, 0xf000
	v_add3_u32 v76, s10, v123, v193
	v_add3_u32 v77, s10, v123, v194
	ds_read2_b32 v[80:81], v76 offset1:16
	ds_read2_b32 v[82:83], v76 offset0:32 offset1:48
	ds_read2_b32 v[84:85], v77 offset1:16
	ds_read2_b32 v[86:87], v77 offset0:32 offset1:48
	v_add_u32_e32 v78, 0x1000, v76
	v_add_u32_e32 v79, 0x1000, v77
	ds_read2_b32 v[88:89], v78 offset1:16
	ds_read2_b32 v[90:91], v78 offset0:32 offset1:48
	ds_read2_b32 v[92:93], v79 offset1:16
	ds_read2_b32 v[94:95], v79 offset0:32 offset1:48
	s_lshl_b64 s[10:11], s[34:35], 4
	s_add_u32 s10, s10, s14
	s_addc_u32 s11, s11, s15
	v_mov_b32_e32 v97, s11
	v_or_b32_e32 v96, s10, v128
	v_lshlrev_b64 v[96:97], 9, v[96:97]
	v_lshlrev_b32_e32 v100, 1, v0
	v_mov_b32_e32 v99, s11
	v_or_b32_e32 v98, s10, v130
	v_lshlrev_b64 v[98:99], 9, v[98:99]
	v_or_b32_e32 v96, v96, v100
	v_or_b32_e32 v98, v98, v100
	v_lshl_add_u64 v[100:101], s[60:61], 0, v[96:97]
	v_lshl_add_u64 v[102:103], s[78:79], 0, v[96:97]
	v_lshl_add_u64 v[104:105], s[60:61], 0, v[98:99]
	v_lshl_add_u64 v[106:107], s[78:79], 0, v[98:99]
	s_waitcnt lgkmcnt(6)
	v_add_f32_e32 v80, v80, v81
	v_add_f32_e32 v82, v82, v83
	v_add_f32_e32 v80, v80, v82
	v_bfe_u32 v81, v80, 16, 1
	v_add3_u32 v80, v80, v81, s88
	global_store_short_d16_hi v[100:101], v80, off
	s_waitcnt lgkmcnt(4)
	v_add_f32_e32 v84, v84, v85
	v_add_f32_e32 v86, v86, v87
	v_add_f32_e32 v84, v84, v86
	v_bfe_u32 v85, v84, 16, 1
	v_add3_u32 v84, v84, v85, s88
	global_store_short_d16_hi v[104:105], v84, off
	s_waitcnt lgkmcnt(2)
	v_add_f32_e32 v88, v88, v89
	v_add_f32_e32 v90, v90, v91
	v_add_f32_e32 v88, v88, v90
	v_bfe_u32 v89, v88, 16, 1
	v_add3_u32 v88, v88, v89, s88
	global_store_short_d16_hi v[102:103], v88, off
	s_waitcnt lgkmcnt(0)
	v_add_f32_e32 v92, v92, v93
	v_add_f32_e32 v94, v94, v95
	v_add_f32_e32 v92, v92, v94
	v_bfe_u32 v93, v92, 16, 1
	v_add3_u32 v92, v92, v93, s88
	global_store_short_d16_hi v[106:107], v92, off

; #define LAS __attribute__((address_space(3)))
; template <int CTRL> __device__ __forceinline__ float dppf(float x) { return __int_as_float(__builtin_amdgcn_mov_dpp(__float_as_int(x), CTRL, 0xF, 0xF, true)); }
; __device__ __forceinline__ void scan_phase(const Params& p, int layer, LAS unsigned char* lds, int tid) {
;     ...
;                 const LAS float* HW = inb + O_HW; const LAS float* HV = inb + O_HV; LAS float* HO = outb + O_HO;
;                 const LAS f32x4* q = (const LAS f32x4*)(HW + kq * 8);
;                 f32x4 f = q[0], qq = q[1]; f32x2 v2 = *(const LAS f32x2*)(HV + r0);
; #pragma unroll
;                 for (int s = 0; s < 16; ++s) {
;                     f32x4 nf = f, nqq = qq; f32x2 nv = v2;
;                     if (s < 15) { const LAS f32x4* qn = (const LAS f32x4*)(HW + ((s + 1) * 16 + kq) * 8); nf = qn[0]; nqq = qn[1]; nv = *(const LAS f32x2*)(HV + (s + 1) * 16 + r0); }
;                     H0 = v2 + (H0 - v2) * f.x; H1 = v2 + (H1 - v2) * f.y; H2 = v2 + (H2 - v2) * f.z; H3 = v2 + (H3 - v2) * f.w;
;                     f32x2 o = (H0 * qq.x + H1 * qq.y) + (H2 * qq.z + H3 * qq.w);
;                     o.x += dppf<0xB1>(o.x); o.y += dppf<0xB1>(o.y); o.x += dppf<0x4E>(o.x); o.y += dppf<0x4E>(o.y);
;                     if ((kq & 3) == 0) *(LAS f32x2*)(HO + (s * 4 + (kq >> 2)) * 16 + r0) = o;
;                     f = nf; qq = nqq; v2 = nv;
;                 }
.LBB0_386:
	v_add_u32_e32 v106, s36, v129
	v_add_u32_e32 v107, s36, v197
	v_mbcnt_lo_u32_b32 v114, -1, 0
	v_mbcnt_hi_u32_b32 v114, -1, v114
	ds_read_b64 v[84:85], v107 offset:29696
	ds_read_b128 v[76:79], v106 offset:21504
	ds_read_b128 v[80:83], v106 offset:21520
	ds_read_b64 v[86:87], v107 offset:29760
	ds_read_b128 v[88:91], v106 offset:22016
	ds_read_b128 v[92:95], v106 offset:22032
	s_add_i32 s10, s33, 0xf000
	v_lshlrev_b32_e32 v114, 3, v114
	v_add3_u32 v3, s10, v131, v197
	v_add_u32_e32 v114, 0x18000, v114
	s_nop 0
	v_cndmask_b32_e64 v3, v114, v3, s[42:43]
	ds_read_b64 v[208:209], v107 offset:29824
	ds_read_b128 v[204:207], v106 offset:22528
	ds_read_b128 v[170:173], v106 offset:22544
	s_waitcnt lgkmcnt(8)
	v_pk_add_f32 v[96:97], v[158:159], v[84:85] neg_lo:[0,1] neg_hi:[0,1]
	v_pk_add_f32 v[98:99], v[160:161], v[84:85] neg_lo:[0,1] neg_hi:[0,1]
	v_pk_add_f32 v[100:101], v[162:163], v[84:85] neg_lo:[0,1] neg_hi:[0,1]
	v_pk_add_f32 v[102:103], v[164:165], v[84:85] neg_lo:[0,1] neg_hi:[0,1]
	s_waitcnt lgkmcnt(7)
	v_pk_fma_f32 v[158:159], v[76:77], v[96:97], v[84:85] op_sel_hi:[0,1,1]
	v_pk_fma_f32 v[160:161], v[76:77], v[98:99], v[84:85] op_sel:[1,0,0]
	s_waitcnt lgkmcnt(6)
	v_pk_mul_f32 v[110:111], v[80:81], v[158:159] op_sel_hi:[0,1]
	v_pk_fma_f32 v[162:163], v[78:79], v[100:101], v[84:85] op_sel_hi:[0,1,1]
	v_pk_fma_f32 v[110:111], v[80:81], v[160:161], v[110:111] op_sel:[1,0,0]
	v_pk_fma_f32 v[164:165], v[78:79], v[102:103], v[84:85] op_sel:[1,0,0]
	v_pk_fma_f32 v[110:111], v[82:83], v[162:163], v[110:111] op_sel_hi:[0,1,1]
	s_nop 0
	v_pk_fma_f32 v[110:111], v[82:83], v[164:165], v[110:111] op_sel:[1,0,0]
	ds_read_b64 v[84:85], v107 offset:29888
	ds_read_b128 v[76:79], v106 offset:23040
	ds_read_b128 v[80:83], v106 offset:23056
	s_waitcnt lgkmcnt(8)
	v_pk_add_f32 v[96:97], v[158:159], v[86:87] neg_lo:[0,1] neg_hi:[0,1]
	v_pk_add_f32 v[98:99], v[160:161], v[86:87] neg_lo:[0,1] neg_hi:[0,1]
	v_pk_add_f32 v[100:101], v[162:163], v[86:87] neg_lo:[0,1] neg_hi:[0,1]
	v_pk_add_f32 v[102:103], v[164:165], v[86:87] neg_lo:[0,1] neg_hi:[0,1]
	v_add_f32_dpp v110, v110, v110 quad_perm:[1,0,3,2] row_mask:0xf bank_mask:0xf bound_ctrl:1
	s_waitcnt lgkmcnt(7)
	v_pk_fma_f32 v[158:159], v[88:89], v[96:97], v[86:87] op_sel_hi:[0,1,1]
	v_add_f32_dpp v111, v111, v111 quad_perm:[1,0,3,2] row_mask:0xf bank_mask:0xf bound_ctrl:1
	v_pk_fma_f32 v[160:161], v[88:89], v[98:99], v[86:87] op_sel:[1,0,0]
	s_waitcnt lgkmcnt(6)
	v_pk_mul_f32 v[112:113], v[92:93], v[158:159] op_sel_hi:[0,1]
	v_pk_fma_f32 v[162:163], v[90:91], v[100:101], v[86:87] op_sel_hi:[0,1,1]
	v_pk_fma_f32 v[112:113], v[92:93], v[160:161], v[112:113] op_sel:[1,0,0]
	v_add_f32_dpp v110, v110, v110 quad_perm:[2,3,0,1] row_mask:0xf bank_mask:0xf bound_ctrl:1
	v_pk_fma_f32 v[164:165], v[90:91], v[102:103], v[86:87] op_sel:[1,0,0]
	v_pk_fma_f32 v[112:113], v[94:95], v[162:163], v[112:113] op_sel_hi:[0,1,1]
	v_add_f32_dpp v111, v111, v111 quad_perm:[2,3,0,1] row_mask:0xf bank_mask:0xf bound_ctrl:1
	ds_write_b64 v3, v[110:111] offset:4096
	v_pk_fma_f32 v[112:113], v[94:95], v[164:165], v[112:113] op_sel:[1,0,0]
	ds_read_b64 v[86:87], v107 offset:29952
	ds_read_b128 v[88:91], v106 offset:23552
	ds_read_b128 v[92:95], v106 offset:23568
	s_waitcnt lgkmcnt(9)
	v_pk_add_f32 v[96:97], v[158:159], v[208:209] neg_lo:[0,1] neg_hi:[0,1]
	v_pk_add_f32 v[98:99], v[160:161], v[208:209] neg_lo:[0,1] neg_hi:[0,1]
	v_pk_add_f32 v[100:101], v[162:163], v[208:209] neg_lo:[0,1] neg_hi:[0,1]
	v_pk_add_f32 v[102:103], v[164:165], v[208:209] neg_lo:[0,1] neg_hi:[0,1]
	v_add_f32_dpp v112, v112, v112 quad_perm:[1,0,3,2] row_mask:0xf bank_mask:0xf bound_ctrl:1
	s_waitcnt lgkmcnt(8)
	v_pk_fma_f32 v[158:159], v[204:205], v[96:97], v[208:209] op_sel_hi:[0,1,1]
	v_add_f32_dpp v113, v113, v113 quad_perm:[1,0,3,2] row_mask:0xf bank_mask:0xf bound_ctrl:1
	v_pk_fma_f32 v[160:161], v[204:205], v[98:99], v[208:209] op_sel:[1,0,0]
	s_waitcnt lgkmcnt(7)
	v_pk_mul_f32 v[110:111], v[170:171], v[158:159] op_sel_hi:[0,1]
	v_pk_fma_f32 v[162:163], v[206:207], v[100:101], v[208:209] op_sel_hi:[0,1,1]
	v_pk_fma_f32 v[110:111], v[170:171], v[160:161], v[110:111] op_sel:[1,0,0]
	v_add_f32_dpp v112, v112, v112 quad_perm:[2,3,0,1] row_mask:0xf bank_mask:0xf bound_ctrl:1
	v_pk_fma_f32 v[164:165], v[206:207], v[102:103], v[208:209] op_sel:[1,0,0]
	v_pk_fma_f32 v[110:111], v[172:173], v[162:163], v[110:111] op_sel_hi:[0,1,1]
	v_add_f32_dpp v113, v113, v113 quad_perm:[2,3,0,1] row_mask:0xf bank_mask:0xf bound_ctrl:1
	ds_write_b64 v3, v[112:113] offset:4352
	v_pk_fma_f32 v[110:111], v[172:173], v[164:165], v[110:111] op_sel:[1,0,0]
	ds_read_b64 v[208:209], v107 offset:30016
	ds_read_b128 v[204:207], v106 offset:24064
	ds_read_b128 v[170:173], v106 offset:24080
	s_waitcnt lgkmcnt(10)
	v_pk_add_f32 v[96:97], v[158:159], v[84:85] neg_lo:[0,1] neg_hi:[0,1]
	v_pk_add_f32 v[98:99], v[160:161], v[84:85] neg_lo:[0,1] neg_hi:[0,1]
	v_pk_add_f32 v[100:101], v[162:163], v[84:85] neg_lo:[0,1] neg_hi:[0,1]
	v_pk_add_f32 v[102:103], v[164:165], v[84:85] neg_lo:[0,1] neg_hi:[0,1]
	v_add_f32_dpp v110, v110, v110 quad_perm:[1,0,3,2] row_mask:0xf bank_mask:0xf bound_ctrl:1
	s_waitcnt lgkmcnt(9)
	v_pk_fma_f32 v[158:159], v[76:77], v[96:97], v[84:85] op_sel_hi:[0,1,1]
	v_add_f32_dpp v111, v111, v111 quad_perm:[1,0,3,2] row_mask:0xf bank_mask:0xf bound_ctrl:1
	v_pk_fma_f32 v[160:161], v[76:77], v[98:99], v[84:85] op_sel:[1,0,0]
	s_waitcnt lgkmcnt(8)
; #define LAS __attribute__((address_space(3)))
; template <int CTRL> __device__ __forceinline__ float dppf(float x) { return __int_as_float(__builtin_amdgcn_mov_dpp(__float_as_int(x), CTRL, 0xF, 0xF, true)); }
; __device__ __forceinline__ void scan_phase(const Params& p, int layer, LAS unsigned char* lds, int tid) {
;     ...
;                 const LAS float* HW = inb + O_HW; const LAS float* HV = inb + O_HV; LAS float* HO = outb + O_HO;
;                 const LAS f32x4* q = (const LAS f32x4*)(HW + kq * 8);
;                 f32x4 f = q[0], qq = q[1]; f32x2 v2 = *(const LAS f32x2*)(HV + r0);
; #pragma unroll
;                 for (int s = 0; s < 16; ++s) {
;                     f32x4 nf = f, nqq = qq; f32x2 nv = v2;
;                     if (s < 15) { const LAS f32x4* qn = (const LAS f32x4*)(HW + ((s + 1) * 16 + kq) * 8); nf = qn[0]; nqq = qn[1]; nv = *(const LAS f32x2*)(HV + (s + 1) * 16 + r0); }
;                     H0 = v2 + (H0 - v2) * f.x; H1 = v2 + (H1 - v2) * f.y; H2 = v2 + (H2 - v2) * f.z; H3 = v2 + (H3 - v2) * f.w;
;                     f32x2 o = (H0 * qq.x + H1 * qq.y) + (H2 * qq.z + H3 * qq.w);
;                     o.x += dppf<0xB1>(o.x); o.y += dppf<0xB1>(o.y); o.x += dppf<0x4E>(o.x); o.y += dppf<0x4E>(o.y);
;                     if ((kq & 3) == 0) *(LAS f32x2*)(HO + (s * 4 + (kq >> 2)) * 16 + r0) = o;
;                     f = nf; qq = nqq; v2 = nv;
;                 }
	v_pk_mul_f32 v[112:113], v[80:81], v[158:159] op_sel_hi:[0,1]
	v_pk_fma_f32 v[162:163], v[78:79], v[100:101], v[84:85] op_sel_hi:[0,1,1]
	v_pk_fma_f32 v[112:113], v[80:81], v[160:161], v[112:113] op_sel:[1,0,0]
	v_add_f32_dpp v110, v110, v110 quad_perm:[2,3,0,1] row_mask:0xf bank_mask:0xf bound_ctrl:1
	v_pk_fma_f32 v[164:165], v[78:79], v[102:103], v[84:85] op_sel:[1,0,0]
	v_pk_fma_f32 v[112:113], v[82:83], v[162:163], v[112:113] op_sel_hi:[0,1,1]
	v_add_f32_dpp v111, v111, v111 quad_perm:[2,3,0,1] row_mask:0xf bank_mask:0xf bound_ctrl:1
	ds_write_b64 v3, v[110:111] offset:4608
	v_pk_fma_f32 v[112:113], v[82:83], v[164:165], v[112:113] op_sel:[1,0,0]
	ds_read_b64 v[84:85], v107 offset:30080
	ds_read_b128 v[76:79], v106 offset:24576
	ds_read_b128 v[80:83], v106 offset:24592
	s_waitcnt lgkmcnt(10)
	v_pk_add_f32 v[96:97], v[158:159], v[86:87] neg_lo:[0,1] neg_hi:[0,1]
	v_pk_add_f32 v[98:99], v[160:161], v[86:87] neg_lo:[0,1] neg_hi:[0,1]
	v_pk_add_f32 v[100:101], v[162:163], v[86:87] neg_lo:[0,1] neg_hi:[0,1]
	v_pk_add_f32 v[102:103], v[164:165], v[86:87] neg_lo:[0,1] neg_hi:[0,1]
	v_add_f32_dpp v112, v112, v112 quad_perm:[1,0,3,2] row_mask:0xf bank_mask:0xf bound_ctrl:1
	s_waitcnt lgkmcnt(9)
	v_pk_fma_f32 v[158:159], v[88:89], v[96:97], v[86:87] op_sel_hi:[0,1,1]
	v_add_f32_dpp v113, v113, v113 quad_perm:[1,0,3,2] row_mask:0xf bank_mask:0xf bound_ctrl:1
	v_pk_fma_f32 v[160:161], v[88:89], v[98:99], v[86:87] op_sel:[1,0,0]
	s_waitcnt lgkmcnt(8)
	v_pk_mul_f32 v[110:111], v[92:93], v[158:159] op_sel_hi:[0,1]
	v_pk_fma_f32 v[162:163], v[90:91], v[100:101], v[86:87] op_sel_hi:[0,1,1]
	v_pk_fma_f32 v[110:111], v[92:93], v[160:161], v[110:111] op_sel:[1,0,0]
	v_add_f32_dpp v112, v112, v112 quad_perm:[2,3,0,1] row_mask:0xf bank_mask:0xf bound_ctrl:1
	v_pk_fma_f32 v[164:165], v[90:91], v[102:103], v[86:87] op_sel:[1,0,0]
	v_pk_fma_f32 v[110:111], v[94:95], v[162:163], v[110:111] op_sel_hi:[0,1,1]
	v_add_f32_dpp v113, v113, v113 quad_perm:[2,3,0,1] row_mask:0xf bank_mask:0xf bound_ctrl:1
	ds_write_b64 v3, v[112:113] offset:4864
	v_pk_fma_f32 v[110:111], v[94:95], v[164:165], v[110:111] op_sel:[1,0,0]
	ds_read_b64 v[86:87], v107 offset:30144
	ds_read_b128 v[88:91], v106 offset:25088
	ds_read_b128 v[92:95], v106 offset:25104
	s_waitcnt lgkmcnt(10)
	v_pk_add_f32 v[96:97], v[158:159], v[208:209] neg_lo:[0,1] neg_hi:[0,1]
	v_pk_add_f32 v[98:99], v[160:161], v[208:209] neg_lo:[0,1] neg_hi:[0,1]
	v_pk_add_f32 v[100:101], v[162:163], v[208:209] neg_lo:[0,1] neg_hi:[0,1]
	v_pk_add_f32 v[102:103], v[164:165], v[208:209] neg_lo:[0,1] neg_hi:[0,1]
	v_add_f32_dpp v110, v110, v110 quad_perm:[1,0,3,2] row_mask:0xf bank_mask:0xf bound_ctrl:1
	s_waitcnt lgkmcnt(9)
	v_pk_fma_f32 v[158:159], v[204:205], v[96:97], v[208:209] op_sel_hi:[0,1,1]
	v_add_f32_dpp v111, v111, v111 quad_perm:[1,0,3,2] row_mask:0xf bank_mask:0xf bound_ctrl:1
	v_pk_fma_f32 v[160:161], v[204:205], v[98:99], v[208:209] op_sel:[1,0,0]
	s_waitcnt lgkmcnt(8)
	v_pk_mul_f32 v[112:113], v[170:171], v[158:159] op_sel_hi:[0,1]
	v_pk_fma_f32 v[162:163], v[206:207], v[100:101], v[208:209] op_sel_hi:[0,1,1]
	v_pk_fma_f32 v[112:113], v[170:171], v[160:161], v[112:113] op_sel:[1,0,0]
	v_add_f32_dpp v110, v110, v110 quad_perm:[2,3,0,1] row_mask:0xf bank_mask:0xf bound_ctrl:1
	v_pk_fma_f32 v[164:165], v[206:207], v[102:103], v[208:209] op_sel:[1,0,0]
	v_pk_fma_f32 v[112:113], v[172:173], v[162:163], v[112:113] op_sel_hi:[0,1,1]
	v_add_f32_dpp v111, v111, v111 quad_perm:[2,3,0,1] row_mask:0xf bank_mask:0xf bound_ctrl:1
	ds_write_b64 v3, v[110:111] offset:5120
	v_pk_fma_f32 v[112:113], v[172:173], v[164:165], v[112:113] op_sel:[1,0,0]
	ds_read_b64 v[208:209], v107 offset:30208
	ds_read_b128 v[204:207], v106 offset:25600
	ds_read_b128 v[170:173], v106 offset:25616
	s_waitcnt lgkmcnt(10)
	v_pk_add_f32 v[96:97], v[158:159], v[84:85] neg_lo:[0,1] neg_hi:[0,1]
	v_pk_add_f32 v[98:99], v[160:161], v[84:85] neg_lo:[0,1] neg_hi:[0,1]
	v_pk_add_f32 v[100:101], v[162:163], v[84:85] neg_lo:[0,1] neg_hi:[0,1]
	v_pk_add_f32 v[102:103], v[164:165], v[84:85] neg_lo:[0,1] neg_hi:[0,1]
	v_add_f32_dpp v112, v112, v112 quad_perm:[1,0,3,2] row_mask:0xf bank_mask:0xf bound_ctrl:1
	s_waitcnt lgkmcnt(9)
	v_pk_fma_f32 v[158:159], v[76:77], v[96:97], v[84:85] op_sel_hi:[0,1,1]
	v_add_f32_dpp v113, v113, v113 quad_perm:[1,0,3,2] row_mask:0xf bank_mask:0xf bound_ctrl:1
	v_pk_fma_f32 v[160:161], v[76:77], v[98:99], v[84:85] op_sel:[1,0,0]
	s_waitcnt lgkmcnt(8)
	v_pk_mul_f32 v[110:111], v[80:81], v[158:159] op_sel_hi:[0,1]
	v_pk_fma_f32 v[162:163], v[78:79], v[100:101], v[84:85] op_sel_hi:[0,1,1]
	v_pk_fma_f32 v[110:111], v[80:81], v[160:161], v[110:111] op_sel:[1,0,0]
	v_add_f32_dpp v112, v112, v112 quad_perm:[2,3,0,1] row_mask:0xf bank_mask:0xf bound_ctrl:1
	v_pk_fma_f32 v[164:165], v[78:79], v[102:103], v[84:85] op_sel:[1,0,0]
	v_pk_fma_f32 v[110:111], v[82:83], v[162:163], v[110:111] op_sel_hi:[0,1,1]
	v_add_f32_dpp v113, v113, v113 quad_perm:[2,3,0,1] row_mask:0xf bank_mask:0xf bound_ctrl:1
	ds_write_b64 v3, v[112:113] offset:5376
	v_pk_fma_f32 v[110:111], v[82:83], v[164:165], v[110:111] op_sel:[1,0,0]
	ds_read_b64 v[84:85], v107 offset:30272
	ds_read_b128 v[76:79], v106 offset:26112
	ds_read_b128 v[80:83], v106 offset:26128
	s_waitcnt lgkmcnt(10)
	v_pk_add_f32 v[96:97], v[158:159], v[86:87] neg_lo:[0,1] neg_hi:[0,1]
	v_pk_add_f32 v[98:99], v[160:161], v[86:87] neg_lo:[0,1] neg_hi:[0,1]
	v_pk_add_f32 v[100:101], v[162:163], v[86:87] neg_lo:[0,1] neg_hi:[0,1]
	v_pk_add_f32 v[102:103], v[164:165], v[86:87] neg_lo:[0,1] neg_hi:[0,1]
	v_add_f32_dpp v110, v110, v110 quad_perm:[1,0,3,2] row_mask:0xf bank_mask:0xf bound_ctrl:1
	s_waitcnt lgkmcnt(9)
; #define LAS __attribute__((address_space(3)))
; template <int CTRL> __device__ __forceinline__ float dppf(float x) { return __int_as_float(__builtin_amdgcn_mov_dpp(__float_as_int(x), CTRL, 0xF, 0xF, true)); }
; __device__ __forceinline__ void scan_phase(const Params& p, int layer, LAS unsigned char* lds, int tid) {
;     ...
;                 const LAS float* HW = inb + O_HW; const LAS float* HV = inb + O_HV; LAS float* HO = outb + O_HO;
;                 const LAS f32x4* q = (const LAS f32x4*)(HW + kq * 8);
;                 f32x4 f = q[0], qq = q[1]; f32x2 v2 = *(const LAS f32x2*)(HV + r0);
; #pragma unroll
;                 for (int s = 0; s < 16; ++s) {
;                     f32x4 nf = f, nqq = qq; f32x2 nv = v2;
;                     if (s < 15) { const LAS f32x4* qn = (const LAS f32x4*)(HW + ((s + 1) * 16 + kq) * 8); nf = qn[0]; nqq = qn[1]; nv = *(const LAS f32x2*)(HV + (s + 1) * 16 + r0); }
;                     H0 = v2 + (H0 - v2) * f.x; H1 = v2 + (H1 - v2) * f.y; H2 = v2 + (H2 - v2) * f.z; H3 = v2 + (H3 - v2) * f.w;
;                     f32x2 o = (H0 * qq.x + H1 * qq.y) + (H2 * qq.z + H3 * qq.w);
;                     o.x += dppf<0xB1>(o.x); o.y += dppf<0xB1>(o.y); o.x += dppf<0x4E>(o.x); o.y += dppf<0x4E>(o.y);
;                     if ((kq & 3) == 0) *(LAS f32x2*)(HO + (s * 4 + (kq >> 2)) * 16 + r0) = o;
;                     f = nf; qq = nqq; v2 = nv;
;                 }
	v_pk_fma_f32 v[158:159], v[88:89], v[96:97], v[86:87] op_sel_hi:[0,1,1]
	v_add_f32_dpp v111, v111, v111 quad_perm:[1,0,3,2] row_mask:0xf bank_mask:0xf bound_ctrl:1
	v_pk_fma_f32 v[160:161], v[88:89], v[98:99], v[86:87] op_sel:[1,0,0]
	s_waitcnt lgkmcnt(8)
	v_pk_mul_f32 v[112:113], v[92:93], v[158:159] op_sel_hi:[0,1]
	v_pk_fma_f32 v[162:163], v[90:91], v[100:101], v[86:87] op_sel_hi:[0,1,1]
	v_pk_fma_f32 v[112:113], v[92:93], v[160:161], v[112:113] op_sel:[1,0,0]
	v_add_f32_dpp v110, v110, v110 quad_perm:[2,3,0,1] row_mask:0xf bank_mask:0xf bound_ctrl:1
	v_pk_fma_f32 v[164:165], v[90:91], v[102:103], v[86:87] op_sel:[1,0,0]
	v_pk_fma_f32 v[112:113], v[94:95], v[162:163], v[112:113] op_sel_hi:[0,1,1]
	v_add_f32_dpp v111, v111, v111 quad_perm:[2,3,0,1] row_mask:0xf bank_mask:0xf bound_ctrl:1
	ds_write_b64 v3, v[110:111] offset:5632
	v_pk_fma_f32 v[112:113], v[94:95], v[164:165], v[112:113] op_sel:[1,0,0]
	ds_read_b64 v[86:87], v107 offset:30336
	ds_read_b128 v[88:91], v106 offset:26624
	ds_read_b128 v[92:95], v106 offset:26640
	s_waitcnt lgkmcnt(10)
	v_pk_add_f32 v[96:97], v[158:159], v[208:209] neg_lo:[0,1] neg_hi:[0,1]
	v_pk_add_f32 v[98:99], v[160:161], v[208:209] neg_lo:[0,1] neg_hi:[0,1]
	v_pk_add_f32 v[100:101], v[162:163], v[208:209] neg_lo:[0,1] neg_hi:[0,1]
	v_pk_add_f32 v[102:103], v[164:165], v[208:209] neg_lo:[0,1] neg_hi:[0,1]
	v_add_f32_dpp v112, v112, v112 quad_perm:[1,0,3,2] row_mask:0xf bank_mask:0xf bound_ctrl:1
	s_waitcnt lgkmcnt(9)
	v_pk_fma_f32 v[158:159], v[204:205], v[96:97], v[208:209] op_sel_hi:[0,1,1]
	v_add_f32_dpp v113, v113, v113 quad_perm:[1,0,3,2] row_mask:0xf bank_mask:0xf bound_ctrl:1
	v_pk_fma_f32 v[160:161], v[204:205], v[98:99], v[208:209] op_sel:[1,0,0]
	s_waitcnt lgkmcnt(8)
	v_pk_mul_f32 v[110:111], v[170:171], v[158:159] op_sel_hi:[0,1]
	v_pk_fma_f32 v[162:163], v[206:207], v[100:101], v[208:209] op_sel_hi:[0,1,1]
	v_pk_fma_f32 v[110:111], v[170:171], v[160:161], v[110:111] op_sel:[1,0,0]
	v_add_f32_dpp v112, v112, v112 quad_perm:[2,3,0,1] row_mask:0xf bank_mask:0xf bound_ctrl:1
	v_pk_fma_f32 v[164:165], v[206:207], v[102:103], v[208:209] op_sel:[1,0,0]
	v_pk_fma_f32 v[110:111], v[172:173], v[162:163], v[110:111] op_sel_hi:[0,1,1]
	v_add_f32_dpp v113, v113, v113 quad_perm:[2,3,0,1] row_mask:0xf bank_mask:0xf bound_ctrl:1
	ds_write_b64 v3, v[112:113] offset:5888
	v_pk_fma_f32 v[110:111], v[172:173], v[164:165], v[110:111] op_sel:[1,0,0]
	ds_read_b64 v[208:209], v107 offset:30400
	ds_read_b128 v[204:207], v106 offset:27136
	ds_read_b128 v[170:173], v106 offset:27152
	s_waitcnt lgkmcnt(10)
	v_pk_add_f32 v[96:97], v[158:159], v[84:85] neg_lo:[0,1] neg_hi:[0,1]
	v_pk_add_f32 v[98:99], v[160:161], v[84:85] neg_lo:[0,1] neg_hi:[0,1]
	v_pk_add_f32 v[100:101], v[162:163], v[84:85] neg_lo:[0,1] neg_hi:[0,1]
	v_pk_add_f32 v[102:103], v[164:165], v[84:85] neg_lo:[0,1] neg_hi:[0,1]
	v_add_f32_dpp v110, v110, v110 quad_perm:[1,0,3,2] row_mask:0xf bank_mask:0xf bound_ctrl:1
	s_waitcnt lgkmcnt(9)
	v_pk_fma_f32 v[158:159], v[76:77], v[96:97], v[84:85] op_sel_hi:[0,1,1]
	v_add_f32_dpp v111, v111, v111 quad_perm:[1,0,3,2] row_mask:0xf bank_mask:0xf bound_ctrl:1
	v_pk_fma_f32 v[160:161], v[76:77], v[98:99], v[84:85] op_sel:[1,0,0]
	s_waitcnt lgkmcnt(8)
	v_pk_mul_f32 v[112:113], v[80:81], v[158:159] op_sel_hi:[0,1]
	v_pk_fma_f32 v[162:163], v[78:79], v[100:101], v[84:85] op_sel_hi:[0,1,1]
	v_pk_fma_f32 v[112:113], v[80:81], v[160:161], v[112:113] op_sel:[1,0,0]
	v_add_f32_dpp v110, v110, v110 quad_perm:[2,3,0,1] row_mask:0xf bank_mask:0xf bound_ctrl:1
	v_pk_fma_f32 v[164:165], v[78:79], v[102:103], v[84:85] op_sel:[1,0,0]
	v_pk_fma_f32 v[112:113], v[82:83], v[162:163], v[112:113] op_sel_hi:[0,1,1]
	v_add_f32_dpp v111, v111, v111 quad_perm:[2,3,0,1] row_mask:0xf bank_mask:0xf bound_ctrl:1
	ds_write_b64 v3, v[110:111] offset:6144
	v_pk_fma_f32 v[112:113], v[82:83], v[164:165], v[112:113] op_sel:[1,0,0]
	ds_read_b64 v[84:85], v107 offset:30464
	ds_read_b128 v[76:79], v106 offset:27648
	ds_read_b128 v[80:83], v106 offset:27664
	s_waitcnt lgkmcnt(10)
	v_pk_add_f32 v[96:97], v[158:159], v[86:87] neg_lo:[0,1] neg_hi:[0,1]
	v_pk_add_f32 v[98:99], v[160:161], v[86:87] neg_lo:[0,1] neg_hi:[0,1]
	v_pk_add_f32 v[100:101], v[162:163], v[86:87] neg_lo:[0,1] neg_hi:[0,1]
	v_pk_add_f32 v[102:103], v[164:165], v[86:87] neg_lo:[0,1] neg_hi:[0,1]
	v_add_f32_dpp v112, v112, v112 quad_perm:[1,0,3,2] row_mask:0xf bank_mask:0xf bound_ctrl:1
	s_waitcnt lgkmcnt(9)
	v_pk_fma_f32 v[158:159], v[88:89], v[96:97], v[86:87] op_sel_hi:[0,1,1]
	v_add_f32_dpp v113, v113, v113 quad_perm:[1,0,3,2] row_mask:0xf bank_mask:0xf bound_ctrl:1
	v_pk_fma_f32 v[160:161], v[88:89], v[98:99], v[86:87] op_sel:[1,0,0]
	s_waitcnt lgkmcnt(8)
	v_pk_mul_f32 v[110:111], v[92:93], v[158:159] op_sel_hi:[0,1]
	v_pk_fma_f32 v[162:163], v[90:91], v[100:101], v[86:87] op_sel_hi:[0,1,1]
	v_pk_fma_f32 v[110:111], v[92:93], v[160:161], v[110:111] op_sel:[1,0,0]
	v_add_f32_dpp v112, v112, v112 quad_perm:[2,3,0,1] row_mask:0xf bank_mask:0xf bound_ctrl:1
	v_pk_fma_f32 v[164:165], v[90:91], v[102:103], v[86:87] op_sel:[1,0,0]
	v_pk_fma_f32 v[110:111], v[94:95], v[162:163], v[110:111] op_sel_hi:[0,1,1]
	v_add_f32_dpp v113, v113, v113 quad_perm:[2,3,0,1] row_mask:0xf bank_mask:0xf bound_ctrl:1
	ds_write_b64 v3, v[112:113] offset:6400
	v_pk_fma_f32 v[110:111], v[94:95], v[164:165], v[110:111] op_sel:[1,0,0]
	ds_read_b64 v[86:87], v107 offset:30528
	ds_read_b128 v[88:91], v106 offset:28160
	ds_read_b128 v[92:95], v106 offset:28176
	s_waitcnt lgkmcnt(10)
; #define LAS __attribute__((address_space(3)))
; template <int CTRL> __device__ __forceinline__ float dppf(float x) { return __int_as_float(__builtin_amdgcn_mov_dpp(__float_as_int(x), CTRL, 0xF, 0xF, true)); }
; __device__ __forceinline__ void scan_phase(const Params& p, int layer, LAS unsigned char* lds, int tid) {
;     ...
;                 const LAS float* HW = inb + O_HW; const LAS float* HV = inb + O_HV; LAS float* HO = outb + O_HO;
;                 const LAS f32x4* q = (const LAS f32x4*)(HW + kq * 8);
;                 f32x4 f = q[0], qq = q[1]; f32x2 v2 = *(const LAS f32x2*)(HV + r0);
; #pragma unroll
;                 for (int s = 0; s < 16; ++s) {
;                     f32x4 nf = f, nqq = qq; f32x2 nv = v2;
;                     if (s < 15) { const LAS f32x4* qn = (const LAS f32x4*)(HW + ((s + 1) * 16 + kq) * 8); nf = qn[0]; nqq = qn[1]; nv = *(const LAS f32x2*)(HV + (s + 1) * 16 + r0); }
;                     H0 = v2 + (H0 - v2) * f.x; H1 = v2 + (H1 - v2) * f.y; H2 = v2 + (H2 - v2) * f.z; H3 = v2 + (H3 - v2) * f.w;
;                     f32x2 o = (H0 * qq.x + H1 * qq.y) + (H2 * qq.z + H3 * qq.w);
;                     o.x += dppf<0xB1>(o.x); o.y += dppf<0xB1>(o.y); o.x += dppf<0x4E>(o.x); o.y += dppf<0x4E>(o.y);
;                     if ((kq & 3) == 0) *(LAS f32x2*)(HO + (s * 4 + (kq >> 2)) * 16 + r0) = o;
;                     f = nf; qq = nqq; v2 = nv;
;                 }
	v_pk_add_f32 v[96:97], v[158:159], v[208:209] neg_lo:[0,1] neg_hi:[0,1]
	v_pk_add_f32 v[98:99], v[160:161], v[208:209] neg_lo:[0,1] neg_hi:[0,1]
	v_pk_add_f32 v[100:101], v[162:163], v[208:209] neg_lo:[0,1] neg_hi:[0,1]
	v_pk_add_f32 v[102:103], v[164:165], v[208:209] neg_lo:[0,1] neg_hi:[0,1]
	v_add_f32_dpp v110, v110, v110 quad_perm:[1,0,3,2] row_mask:0xf bank_mask:0xf bound_ctrl:1
	s_waitcnt lgkmcnt(9)
	v_pk_fma_f32 v[158:159], v[204:205], v[96:97], v[208:209] op_sel_hi:[0,1,1]
	v_add_f32_dpp v111, v111, v111 quad_perm:[1,0,3,2] row_mask:0xf bank_mask:0xf bound_ctrl:1
	v_pk_fma_f32 v[160:161], v[204:205], v[98:99], v[208:209] op_sel:[1,0,0]
	s_waitcnt lgkmcnt(8)
	v_pk_mul_f32 v[112:113], v[170:171], v[158:159] op_sel_hi:[0,1]
	v_pk_fma_f32 v[162:163], v[206:207], v[100:101], v[208:209] op_sel_hi:[0,1,1]
	v_pk_fma_f32 v[112:113], v[170:171], v[160:161], v[112:113] op_sel:[1,0,0]
	v_add_f32_dpp v110, v110, v110 quad_perm:[2,3,0,1] row_mask:0xf bank_mask:0xf bound_ctrl:1
	v_pk_fma_f32 v[164:165], v[206:207], v[102:103], v[208:209] op_sel:[1,0,0]
	v_pk_fma_f32 v[112:113], v[172:173], v[162:163], v[112:113] op_sel_hi:[0,1,1]
	v_add_f32_dpp v111, v111, v111 quad_perm:[2,3,0,1] row_mask:0xf bank_mask:0xf bound_ctrl:1
	ds_write_b64 v3, v[110:111] offset:6656
	v_pk_fma_f32 v[112:113], v[172:173], v[164:165], v[112:113] op_sel:[1,0,0]
	ds_read_b64 v[208:209], v107 offset:30592
	ds_read_b128 v[204:207], v106 offset:28672
	ds_read_b128 v[170:173], v106 offset:28688
	s_waitcnt lgkmcnt(10)
	v_pk_add_f32 v[96:97], v[158:159], v[84:85] neg_lo:[0,1] neg_hi:[0,1]
	v_pk_add_f32 v[98:99], v[160:161], v[84:85] neg_lo:[0,1] neg_hi:[0,1]
	v_pk_add_f32 v[100:101], v[162:163], v[84:85] neg_lo:[0,1] neg_hi:[0,1]
	v_pk_add_f32 v[102:103], v[164:165], v[84:85] neg_lo:[0,1] neg_hi:[0,1]
	v_add_f32_dpp v112, v112, v112 quad_perm:[1,0,3,2] row_mask:0xf bank_mask:0xf bound_ctrl:1
	s_waitcnt lgkmcnt(9)
	v_pk_fma_f32 v[158:159], v[76:77], v[96:97], v[84:85] op_sel_hi:[0,1,1]
	v_add_f32_dpp v113, v113, v113 quad_perm:[1,0,3,2] row_mask:0xf bank_mask:0xf bound_ctrl:1
	v_pk_fma_f32 v[160:161], v[76:77], v[98:99], v[84:85] op_sel:[1,0,0]
	s_waitcnt lgkmcnt(8)
	v_pk_mul_f32 v[110:111], v[80:81], v[158:159] op_sel_hi:[0,1]
	v_pk_fma_f32 v[162:163], v[78:79], v[100:101], v[84:85] op_sel_hi:[0,1,1]
	v_pk_fma_f32 v[110:111], v[80:81], v[160:161], v[110:111] op_sel:[1,0,0]
	v_add_f32_dpp v112, v112, v112 quad_perm:[2,3,0,1] row_mask:0xf bank_mask:0xf bound_ctrl:1
	v_pk_fma_f32 v[164:165], v[78:79], v[102:103], v[84:85] op_sel:[1,0,0]
	v_pk_fma_f32 v[110:111], v[82:83], v[162:163], v[110:111] op_sel_hi:[0,1,1]
	v_add_f32_dpp v113, v113, v113 quad_perm:[2,3,0,1] row_mask:0xf bank_mask:0xf bound_ctrl:1
	ds_write_b64 v3, v[112:113] offset:6912
	v_pk_fma_f32 v[110:111], v[82:83], v[164:165], v[110:111] op_sel:[1,0,0]
	ds_read_b64 v[84:85], v107 offset:30656
	ds_read_b128 v[76:79], v106 offset:29184
	ds_read_b128 v[80:83], v106 offset:29200
	s_waitcnt lgkmcnt(10)
	v_pk_add_f32 v[96:97], v[158:159], v[86:87] neg_lo:[0,1] neg_hi:[0,1]
	v_pk_add_f32 v[98:99], v[160:161], v[86:87] neg_lo:[0,1] neg_hi:[0,1]
	v_pk_add_f32 v[100:101], v[162:163], v[86:87] neg_lo:[0,1] neg_hi:[0,1]
	v_pk_add_f32 v[102:103], v[164:165], v[86:87] neg_lo:[0,1] neg_hi:[0,1]
	v_add_f32_dpp v110, v110, v110 quad_perm:[1,0,3,2] row_mask:0xf bank_mask:0xf bound_ctrl:1
	s_waitcnt lgkmcnt(9)
	v_pk_fma_f32 v[158:159], v[88:89], v[96:97], v[86:87] op_sel_hi:[0,1,1]
	v_add_f32_dpp v111, v111, v111 quad_perm:[1,0,3,2] row_mask:0xf bank_mask:0xf bound_ctrl:1
	v_pk_fma_f32 v[160:161], v[88:89], v[98:99], v[86:87] op_sel:[1,0,0]
	s_waitcnt lgkmcnt(8)
; #define LAS __attribute__((address_space(3)))
; template <int CTRL> __device__ __forceinline__ float dppf(float x) { return __int_as_float(__builtin_amdgcn_mov_dpp(__float_as_int(x), CTRL, 0xF, 0xF, true)); }
; __device__ __forceinline__ void scan_phase(const Params& p, int layer, LAS unsigned char* lds, int tid) {
;     ...
;                 const LAS float* HW = inb + O_HW; const LAS float* HV = inb + O_HV; LAS float* HO = outb + O_HO;
;                 const LAS f32x4* q = (const LAS f32x4*)(HW + kq * 8);
;                 f32x4 f = q[0], qq = q[1]; f32x2 v2 = *(const LAS f32x2*)(HV + r0);
; #pragma unroll
;                 for (int s = 0; s < 16; ++s) {
;                     f32x4 nf = f, nqq = qq; f32x2 nv = v2;
;                     if (s < 15) { const LAS f32x4* qn = (const LAS f32x4*)(HW + ((s + 1) * 16 + kq) * 8); nf = qn[0]; nqq = qn[1]; nv = *(const LAS f32x2*)(HV + (s + 1) * 16 + r0); }
;                     H0 = v2 + (H0 - v2) * f.x; H1 = v2 + (H1 - v2) * f.y; H2 = v2 + (H2 - v2) * f.z; H3 = v2 + (H3 - v2) * f.w;
;                     f32x2 o = (H0 * qq.x + H1 * qq.y) + (H2 * qq.z + H3 * qq.w);
;                     o.x += dppf<0xB1>(o.x); o.y += dppf<0xB1>(o.y); o.x += dppf<0x4E>(o.x); o.y += dppf<0x4E>(o.y);
;                     if ((kq & 3) == 0) *(LAS f32x2*)(HO + (s * 4 + (kq >> 2)) * 16 + r0) = o;
;                     f = nf; qq = nqq; v2 = nv;
;                 }
	v_pk_mul_f32 v[112:113], v[92:93], v[158:159] op_sel_hi:[0,1]
	v_pk_fma_f32 v[162:163], v[90:91], v[100:101], v[86:87] op_sel_hi:[0,1,1]
	v_pk_fma_f32 v[112:113], v[92:93], v[160:161], v[112:113] op_sel:[1,0,0]
	v_add_f32_dpp v110, v110, v110 quad_perm:[2,3,0,1] row_mask:0xf bank_mask:0xf bound_ctrl:1
	v_pk_fma_f32 v[164:165], v[90:91], v[102:103], v[86:87] op_sel:[1,0,0]
	v_pk_fma_f32 v[112:113], v[94:95], v[162:163], v[112:113] op_sel_hi:[0,1,1]
	v_add_f32_dpp v111, v111, v111 quad_perm:[2,3,0,1] row_mask:0xf bank_mask:0xf bound_ctrl:1
	ds_write_b64 v3, v[110:111] offset:7168
	v_pk_fma_f32 v[112:113], v[94:95], v[164:165], v[112:113] op_sel:[1,0,0]
	s_waitcnt lgkmcnt(7)
	v_pk_add_f32 v[96:97], v[158:159], v[208:209] neg_lo:[0,1] neg_hi:[0,1]
	v_pk_add_f32 v[98:99], v[160:161], v[208:209] neg_lo:[0,1] neg_hi:[0,1]
	v_pk_add_f32 v[100:101], v[162:163], v[208:209] neg_lo:[0,1] neg_hi:[0,1]
	v_pk_add_f32 v[102:103], v[164:165], v[208:209] neg_lo:[0,1] neg_hi:[0,1]
	v_add_f32_dpp v112, v112, v112 quad_perm:[1,0,3,2] row_mask:0xf bank_mask:0xf bound_ctrl:1
	s_waitcnt lgkmcnt(6)
	v_pk_fma_f32 v[158:159], v[204:205], v[96:97], v[208:209] op_sel_hi:[0,1,1]
	v_add_f32_dpp v113, v113, v113 quad_perm:[1,0,3,2] row_mask:0xf bank_mask:0xf bound_ctrl:1
	v_pk_fma_f32 v[160:161], v[204:205], v[98:99], v[208:209] op_sel:[1,0,0]
	s_waitcnt lgkmcnt(5)
	v_pk_mul_f32 v[110:111], v[170:171], v[158:159] op_sel_hi:[0,1]
	v_pk_fma_f32 v[162:163], v[206:207], v[100:101], v[208:209] op_sel_hi:[0,1,1]
	v_pk_fma_f32 v[110:111], v[170:171], v[160:161], v[110:111] op_sel:[1,0,0]
	v_add_f32_dpp v112, v112, v112 quad_perm:[2,3,0,1] row_mask:0xf bank_mask:0xf bound_ctrl:1
	v_pk_fma_f32 v[164:165], v[206:207], v[102:103], v[208:209] op_sel:[1,0,0]
	v_pk_fma_f32 v[110:111], v[172:173], v[162:163], v[110:111] op_sel_hi:[0,1,1]
	v_add_f32_dpp v113, v113, v113 quad_perm:[2,3,0,1] row_mask:0xf bank_mask:0xf bound_ctrl:1
	ds_write_b64 v3, v[112:113] offset:7424
	v_pk_fma_f32 v[110:111], v[172:173], v[164:165], v[110:111] op_sel:[1,0,0]
	s_waitcnt lgkmcnt(4)
	v_pk_add_f32 v[96:97], v[158:159], v[84:85] neg_lo:[0,1] neg_hi:[0,1]
	v_pk_add_f32 v[98:99], v[160:161], v[84:85] neg_lo:[0,1] neg_hi:[0,1]
	v_pk_add_f32 v[100:101], v[162:163], v[84:85] neg_lo:[0,1] neg_hi:[0,1]
	v_pk_add_f32 v[102:103], v[164:165], v[84:85] neg_lo:[0,1] neg_hi:[0,1]
	v_add_f32_dpp v110, v110, v110 quad_perm:[1,0,3,2] row_mask:0xf bank_mask:0xf bound_ctrl:1
	s_waitcnt lgkmcnt(3)
	v_pk_fma_f32 v[158:159], v[76:77], v[96:97], v[84:85] op_sel_hi:[0,1,1]
	v_add_f32_dpp v111, v111, v111 quad_perm:[1,0,3,2] row_mask:0xf bank_mask:0xf bound_ctrl:1
	v_pk_fma_f32 v[160:161], v[76:77], v[98:99], v[84:85] op_sel:[1,0,0]
	s_waitcnt lgkmcnt(2)
	v_pk_mul_f32 v[112:113], v[80:81], v[158:159] op_sel_hi:[0,1]
	v_pk_fma_f32 v[162:163], v[78:79], v[100:101], v[84:85] op_sel_hi:[0,1,1]
	v_pk_fma_f32 v[112:113], v[80:81], v[160:161], v[112:113] op_sel:[1,0,0]
	v_add_f32_dpp v110, v110, v110 quad_perm:[2,3,0,1] row_mask:0xf bank_mask:0xf bound_ctrl:1
	v_pk_fma_f32 v[164:165], v[78:79], v[102:103], v[84:85] op_sel:[1,0,0]
	v_pk_fma_f32 v[112:113], v[82:83], v[162:163], v[112:113] op_sel_hi:[0,1,1]
	v_add_f32_dpp v111, v111, v111 quad_perm:[2,3,0,1] row_mask:0xf bank_mask:0xf bound_ctrl:1
	ds_write_b64 v3, v[110:111] offset:7680
	v_pk_fma_f32 v[112:113], v[82:83], v[164:165], v[112:113] op_sel:[1,0,0]
	s_nop 1
	s_nop 0
	v_add_f32_dpp v112, v112, v112 quad_perm:[1,0,3,2] row_mask:0xf bank_mask:0xf bound_ctrl:1
	v_add_f32_dpp v113, v113, v113 quad_perm:[1,0,3,2] row_mask:0xf bank_mask:0xf bound_ctrl:1
	s_nop 0
	v_add_f32_dpp v112, v112, v112 quad_perm:[2,3,0,1] row_mask:0xf bank_mask:0xf bound_ctrl:1
	v_add_f32_dpp v113, v113, v113 quad_perm:[2,3,0,1] row_mask:0xf bank_mask:0xf bound_ctrl:1
	ds_write_b64 v3, v[112:113] offset:7936

; #define LAS __attribute__((address_space(3)))
; template <int CTRL> __device__ __forceinline__ float dppf(float x) { return __int_as_float(__builtin_amdgcn_mov_dpp(__float_as_int(x), CTRL, 0xF, 0xF, true)); }
; __device__ __forceinline__ void scan_phase(const Params& p, int layer, LAS unsigned char* lds, int tid) {
;     ...
;                 const LAS float* RW = inb; const LAS float* RV = inb + O_RV; LAS float* RO = outb;
;                 const LAS f32x4* q = (const LAS f32x4*)(RW + kq * 20);
;                 f32x4 kk = q[0], w = q[1], bb = q[2], k = q[3], r = q[4]; float v = RV[rrow];
; #pragma unroll
;                 for (int s = 0; s < 16; ++s) {
;                     f32x4 nkk = kk, nw = w, nbb = bb, nk = k, nr = r; float nv = v;
;                     if (s < 15) { const LAS f32x4* qn = (const LAS f32x4*)(RW + ((s + 1) * 16 + kq) * 20);
;                         nkk = qn[0]; nw = qn[1]; nbb = qn[2]; nk = qn[3]; nr = qn[4]; nv = RV[(s + 1) * 16 + rrow]; }
;                     const f32x2 p2 = S01 * kk.xy + S23 * kk.zw;
;                     float pd = p2.x + p2.y;
;                     const f32x2 a01 = S01 * w.xy + k.xy * v, a23 = S23 * w.zw + k.zw * v;
;                     pd = row16_sum(pd);
;                     S01 = a01 - bb.xy * pd; S23 = a23 - bb.zw * pd;
;                     const f32x2 o2 = S01 * r.xy + S23 * r.zw;
;                     float o = o2.x + o2.y;
;                     o += dppf<0xB1>(o); o += dppf<0x4E>(o);
;                     if ((kq & 3) == 0) RO[(s * 4 + (kq >> 2)) * 16 + rrow] = o;
;                     kk = nkk; w = nw; bb = nbb; k = nk; r = nr; v = nv;
;                 }
.LBB0_420:
	s_andn2_saveexec_b64 s[18:19], s[18:19]
	s_cbranch_execz .LBB0_280
	v_add_u32_e32 v204, s36, v189
	v_add_u32_e32 v205, s36, v198
	v_mbcnt_lo_u32_b32 v209, -1, 0
	v_mbcnt_hi_u32_b32 v209, -1, v209
	ds_read_b128 v[76:79], v204 offset:0
	ds_read_b128 v[80:83], v204 offset:16
	ds_read_b128 v[88:91], v204 offset:48
	ds_read_b32 v166, v205 offset:20480
	ds_read_b128 v[84:87], v204 offset:32
	ds_read_b128 v[92:95], v204 offset:64
	v_lshlrev_b32_e32 v209, 2, v209
	v_add3_u32 v3, s33, v131, v198
	v_add_u32_e32 v209, 0x8000, v209
	s_nop 0
	v_cndmask_b32_e64 v3, v209, v3, s[42:43]
	ds_read_b128 v[96:99], v204 offset:1280
	ds_read_b128 v[100:103], v204 offset:1296
	ds_read_b128 v[108:111], v204 offset:1328
	ds_read_b32 v168, v205 offset:20544
	ds_read_b128 v[104:107], v204 offset:1312
	s_waitcnt lgkmcnt(10)
	v_mul_f32_e32 v206, v76, v114
	v_fmac_f32_e32 v206, v77, v115
	v_fmac_f32_e32 v206, v78, v112
	v_fmac_f32_e32 v206, v79, v113
	ds_read_b128 v[158:161], v204 offset:1344
	s_waitcnt lgkmcnt(10)
	v_pk_mul_f32 v[164:165], v[80:81], v[114:115]
	v_pk_mul_f32 v[170:171], v[82:83], v[112:113]
	v_add_f32_dpp v206, v206, v206 quad_perm:[1,0,3,2] row_mask:0xf bank_mask:0xf bound_ctrl:1
	s_waitcnt lgkmcnt(8)
	v_pk_fma_f32 v[164:165], v[88:89], v[166:167], v[164:165] op_sel_hi:[1,0,1]
	v_add_f32_dpp v206, v206, v206 quad_perm:[2,3,0,1] row_mask:0xf bank_mask:0xf bound_ctrl:1
	v_pk_fma_f32 v[170:171], v[90:91], v[166:167], v[170:171] op_sel_hi:[1,0,1]
	s_nop 0
	v_add_f32_dpp v206, v206, v206 row_half_mirror row_mask:0xf bank_mask:0xf bound_ctrl:1
	s_nop 1
	s_nop 0
	v_add_f32_dpp v206, v206, v206 row_mirror row_mask:0xf bank_mask:0xf bound_ctrl:1
	s_waitcnt lgkmcnt(7)
	v_pk_fma_f32 v[114:115], v[84:85], v[206:207], v[164:165] op_sel_hi:[1,0,1] neg_lo:[1,0,0] neg_hi:[1,0,0]
	v_pk_fma_f32 v[112:113], v[86:87], v[206:207], v[170:171] op_sel_hi:[1,0,1] neg_lo:[1,0,0] neg_hi:[1,0,0]
	ds_read_b128 v[76:79], v204 offset:2560
	ds_read_b128 v[80:83], v204 offset:2576
	ds_read_b128 v[88:91], v204 offset:2608
	ds_read_b32 v166, v205 offset:20608
	ds_read_b128 v[84:87], v204 offset:2592
	s_waitcnt lgkmcnt(10)
	v_mul_f32_e32 v206, v96, v114
	v_mul_f32_e32 v208, v92, v114
	v_fmac_f32_e32 v206, v97, v115
	v_fmac_f32_e32 v208, v93, v115
	v_fmac_f32_e32 v206, v98, v112
	v_fmac_f32_e32 v208, v94, v112
	v_fmac_f32_e32 v206, v99, v113
	v_fmac_f32_e32 v208, v95, v113
	ds_read_b128 v[92:95], v204 offset:2624
	s_waitcnt lgkmcnt(10)
	v_pk_mul_f32 v[164:165], v[100:101], v[114:115]
	v_pk_mul_f32 v[170:171], v[102:103], v[112:113]
	v_add_f32_dpp v206, v206, v206 quad_perm:[1,0,3,2] row_mask:0xf bank_mask:0xf bound_ctrl:1
	v_add_f32_dpp v208, v208, v208 quad_perm:[1,0,3,2] row_mask:0xf bank_mask:0xf bound_ctrl:1
	s_waitcnt lgkmcnt(8)
	v_pk_fma_f32 v[164:165], v[108:109], v[168:169], v[164:165] op_sel_hi:[1,0,1]
	v_add_f32_dpp v206, v206, v206 quad_perm:[2,3,0,1] row_mask:0xf bank_mask:0xf bound_ctrl:1
	v_pk_fma_f32 v[170:171], v[110:111], v[168:169], v[170:171] op_sel_hi:[1,0,1]
	v_add_f32_dpp v208, v208, v208 quad_perm:[2,3,0,1] row_mask:0xf bank_mask:0xf bound_ctrl:1
	v_add_f32_dpp v206, v206, v206 row_half_mirror row_mask:0xf bank_mask:0xf bound_ctrl:1
	s_nop 0
	ds_write_b32 v3, v208 offset:61440
	v_add_f32_dpp v206, v206, v206 row_mirror row_mask:0xf bank_mask:0xf bound_ctrl:1
	s_waitcnt lgkmcnt(8)
	v_pk_fma_f32 v[114:115], v[104:105], v[206:207], v[164:165] op_sel_hi:[1,0,1] neg_lo:[1,0,0] neg_hi:[1,0,0]
	v_pk_fma_f32 v[112:113], v[106:107], v[206:207], v[170:171] op_sel_hi:[1,0,1] neg_lo:[1,0,0] neg_hi:[1,0,0]
	ds_read_b128 v[96:99], v204 offset:3840
	ds_read_b128 v[100:103], v204 offset:3856
	ds_read_b128 v[108:111], v204 offset:3888
	ds_read_b32 v168, v205 offset:20672
	ds_read_b128 v[104:107], v204 offset:3872
	s_waitcnt lgkmcnt(11)
	v_mul_f32_e32 v206, v76, v114
	v_mul_f32_e32 v208, v158, v114
	v_fmac_f32_e32 v206, v77, v115
	v_fmac_f32_e32 v208, v159, v115
	v_fmac_f32_e32 v206, v78, v112
	v_fmac_f32_e32 v208, v160, v112
	v_fmac_f32_e32 v206, v79, v113
	v_fmac_f32_e32 v208, v161, v113
	ds_read_b128 v[158:161], v204 offset:3904
	s_waitcnt lgkmcnt(11)
	v_pk_mul_f32 v[164:165], v[80:81], v[114:115]
	v_pk_mul_f32 v[170:171], v[82:83], v[112:113]
	v_add_f32_dpp v206, v206, v206 quad_perm:[1,0,3,2] row_mask:0xf bank_mask:0xf bound_ctrl:1
	v_add_f32_dpp v208, v208, v208 quad_perm:[1,0,3,2] row_mask:0xf bank_mask:0xf bound_ctrl:1
	s_waitcnt lgkmcnt(9)
	v_pk_fma_f32 v[164:165], v[88:89], v[166:167], v[164:165] op_sel_hi:[1,0,1]
	v_add_f32_dpp v206, v206, v206 quad_perm:[2,3,0,1] row_mask:0xf bank_mask:0xf bound_ctrl:1
	v_pk_fma_f32 v[170:171], v[90:91], v[166:167], v[170:171] op_sel_hi:[1,0,1]
	v_add_f32_dpp v208, v208, v208 quad_perm:[2,3,0,1] row_mask:0xf bank_mask:0xf bound_ctrl:1
	v_add_f32_dpp v206, v206, v206 row_half_mirror row_mask:0xf bank_mask:0xf bound_ctrl:1
	s_nop 0
	ds_write_b32 v3, v208 offset:61696
	v_add_f32_dpp v206, v206, v206 row_mirror row_mask:0xf bank_mask:0xf bound_ctrl:1
	s_waitcnt lgkmcnt(9)
	v_pk_fma_f32 v[114:115], v[84:85], v[206:207], v[164:165] op_sel_hi:[1,0,1] neg_lo:[1,0,0] neg_hi:[1,0,0]
	v_pk_fma_f32 v[112:113], v[86:87], v[206:207], v[170:171] op_sel_hi:[1,0,1] neg_lo:[1,0,0] neg_hi:[1,0,0]
	ds_read_b128 v[76:79], v204 offset:5120
	ds_read_b128 v[80:83], v204 offset:5136
	ds_read_b128 v[88:91], v204 offset:5168
	ds_read_b32 v166, v205 offset:20736
	ds_read_b128 v[84:87], v204 offset:5152
	s_waitcnt lgkmcnt(11)
	v_mul_f32_e32 v206, v96, v114
	v_mul_f32_e32 v208, v92, v114
	v_fmac_f32_e32 v206, v97, v115
	v_fmac_f32_e32 v208, v93, v115
	v_fmac_f32_e32 v206, v98, v112
	v_fmac_f32_e32 v208, v94, v112
	v_fmac_f32_e32 v206, v99, v113
	v_fmac_f32_e32 v208, v95, v113
	ds_read_b128 v[92:95], v204 offset:5184
	s_waitcnt lgkmcnt(11)
; #define LAS __attribute__((address_space(3)))
; template <int CTRL> __device__ __forceinline__ float dppf(float x) { return __int_as_float(__builtin_amdgcn_mov_dpp(__float_as_int(x), CTRL, 0xF, 0xF, true)); }
; __device__ __forceinline__ void scan_phase(const Params& p, int layer, LAS unsigned char* lds, int tid) {
;     ...
;                 const LAS float* RW = inb; const LAS float* RV = inb + O_RV; LAS float* RO = outb;
;                 const LAS f32x4* q = (const LAS f32x4*)(RW + kq * 20);
;                 f32x4 kk = q[0], w = q[1], bb = q[2], k = q[3], r = q[4]; float v = RV[rrow];
; #pragma unroll
;                 for (int s = 0; s < 16; ++s) {
;                     f32x4 nkk = kk, nw = w, nbb = bb, nk = k, nr = r; float nv = v;
;                     if (s < 15) { const LAS f32x4* qn = (const LAS f32x4*)(RW + ((s + 1) * 16 + kq) * 20);
;                         nkk = qn[0]; nw = qn[1]; nbb = qn[2]; nk = qn[3]; nr = qn[4]; nv = RV[(s + 1) * 16 + rrow]; }
;                     const f32x2 p2 = S01 * kk.xy + S23 * kk.zw;
;                     float pd = p2.x + p2.y;
;                     const f32x2 a01 = S01 * w.xy + k.xy * v, a23 = S23 * w.zw + k.zw * v;
;                     pd = row16_sum(pd);
;                     S01 = a01 - bb.xy * pd; S23 = a23 - bb.zw * pd;
;                     const f32x2 o2 = S01 * r.xy + S23 * r.zw;
;                     float o = o2.x + o2.y;
;                     o += dppf<0xB1>(o); o += dppf<0x4E>(o);
;                     if ((kq & 3) == 0) RO[(s * 4 + (kq >> 2)) * 16 + rrow] = o;
;                     kk = nkk; w = nw; bb = nbb; k = nk; r = nr; v = nv;
;                 }
	v_pk_mul_f32 v[164:165], v[100:101], v[114:115]
	v_pk_mul_f32 v[170:171], v[102:103], v[112:113]
	v_add_f32_dpp v206, v206, v206 quad_perm:[1,0,3,2] row_mask:0xf bank_mask:0xf bound_ctrl:1
	v_add_f32_dpp v208, v208, v208 quad_perm:[1,0,3,2] row_mask:0xf bank_mask:0xf bound_ctrl:1
	s_waitcnt lgkmcnt(9)
	v_pk_fma_f32 v[164:165], v[108:109], v[168:169], v[164:165] op_sel_hi:[1,0,1]
	v_add_f32_dpp v206, v206, v206 quad_perm:[2,3,0,1] row_mask:0xf bank_mask:0xf bound_ctrl:1
	v_pk_fma_f32 v[170:171], v[110:111], v[168:169], v[170:171] op_sel_hi:[1,0,1]
	v_add_f32_dpp v208, v208, v208 quad_perm:[2,3,0,1] row_mask:0xf bank_mask:0xf bound_ctrl:1
	v_add_f32_dpp v206, v206, v206 row_half_mirror row_mask:0xf bank_mask:0xf bound_ctrl:1
	s_nop 0
	ds_write_b32 v3, v208 offset:61952
	v_add_f32_dpp v206, v206, v206 row_mirror row_mask:0xf bank_mask:0xf bound_ctrl:1
	s_waitcnt lgkmcnt(9)
	v_pk_fma_f32 v[114:115], v[104:105], v[206:207], v[164:165] op_sel_hi:[1,0,1] neg_lo:[1,0,0] neg_hi:[1,0,0]
	v_pk_fma_f32 v[112:113], v[106:107], v[206:207], v[170:171] op_sel_hi:[1,0,1] neg_lo:[1,0,0] neg_hi:[1,0,0]
	ds_read_b128 v[96:99], v204 offset:6400
	ds_read_b128 v[100:103], v204 offset:6416
	ds_read_b128 v[108:111], v204 offset:6448
	ds_read_b32 v168, v205 offset:20800
	ds_read_b128 v[104:107], v204 offset:6432
	s_waitcnt lgkmcnt(11)
	v_mul_f32_e32 v206, v76, v114
	v_mul_f32_e32 v208, v158, v114
	v_fmac_f32_e32 v206, v77, v115
	v_fmac_f32_e32 v208, v159, v115
	v_fmac_f32_e32 v206, v78, v112
	v_fmac_f32_e32 v208, v160, v112
	v_fmac_f32_e32 v206, v79, v113
	v_fmac_f32_e32 v208, v161, v113
	ds_read_b128 v[158:161], v204 offset:6464
	s_waitcnt lgkmcnt(11)
	v_pk_mul_f32 v[164:165], v[80:81], v[114:115]
	v_pk_mul_f32 v[170:171], v[82:83], v[112:113]
	v_add_f32_dpp v206, v206, v206 quad_perm:[1,0,3,2] row_mask:0xf bank_mask:0xf bound_ctrl:1
	v_add_f32_dpp v208, v208, v208 quad_perm:[1,0,3,2] row_mask:0xf bank_mask:0xf bound_ctrl:1
	s_waitcnt lgkmcnt(9)
	v_pk_fma_f32 v[164:165], v[88:89], v[166:167], v[164:165] op_sel_hi:[1,0,1]
	v_add_f32_dpp v206, v206, v206 quad_perm:[2,3,0,1] row_mask:0xf bank_mask:0xf bound_ctrl:1
	v_pk_fma_f32 v[170:171], v[90:91], v[166:167], v[170:171] op_sel_hi:[1,0,1]
	v_add_f32_dpp v208, v208, v208 quad_perm:[2,3,0,1] row_mask:0xf bank_mask:0xf bound_ctrl:1
	v_add_f32_dpp v206, v206, v206 row_half_mirror row_mask:0xf bank_mask:0xf bound_ctrl:1
	s_nop 0
	ds_write_b32 v3, v208 offset:62208
	v_add_f32_dpp v206, v206, v206 row_mirror row_mask:0xf bank_mask:0xf bound_ctrl:1
	s_waitcnt lgkmcnt(9)
	v_pk_fma_f32 v[114:115], v[84:85], v[206:207], v[164:165] op_sel_hi:[1,0,1] neg_lo:[1,0,0] neg_hi:[1,0,0]
	v_pk_fma_f32 v[112:113], v[86:87], v[206:207], v[170:171] op_sel_hi:[1,0,1] neg_lo:[1,0,0] neg_hi:[1,0,0]
	ds_read_b128 v[76:79], v204 offset:7680
	ds_read_b128 v[80:83], v204 offset:7696
	ds_read_b128 v[88:91], v204 offset:7728
	ds_read_b32 v166, v205 offset:20864
	ds_read_b128 v[84:87], v204 offset:7712
	s_waitcnt lgkmcnt(11)
	v_mul_f32_e32 v206, v96, v114
	v_mul_f32_e32 v208, v92, v114
	v_fmac_f32_e32 v206, v97, v115
	v_fmac_f32_e32 v208, v93, v115
	v_fmac_f32_e32 v206, v98, v112
	v_fmac_f32_e32 v208, v94, v112
	v_fmac_f32_e32 v206, v99, v113
	v_fmac_f32_e32 v208, v95, v113
	ds_read_b128 v[92:95], v204 offset:7744
	s_waitcnt lgkmcnt(11)
	v_pk_mul_f32 v[164:165], v[100:101], v[114:115]
	v_pk_mul_f32 v[170:171], v[102:103], v[112:113]
	v_add_f32_dpp v206, v206, v206 quad_perm:[1,0,3,2] row_mask:0xf bank_mask:0xf bound_ctrl:1
	v_add_f32_dpp v208, v208, v208 quad_perm:[1,0,3,2] row_mask:0xf bank_mask:0xf bound_ctrl:1
	s_waitcnt lgkmcnt(9)
	v_pk_fma_f32 v[164:165], v[108:109], v[168:169], v[164:165] op_sel_hi:[1,0,1]
	v_add_f32_dpp v206, v206, v206 quad_perm:[2,3,0,1] row_mask:0xf bank_mask:0xf bound_ctrl:1
	v_pk_fma_f32 v[170:171], v[110:111], v[168:169], v[170:171] op_sel_hi:[1,0,1]
	v_add_f32_dpp v208, v208, v208 quad_perm:[2,3,0,1] row_mask:0xf bank_mask:0xf bound_ctrl:1
	v_add_f32_dpp v206, v206, v206 row_half_mirror row_mask:0xf bank_mask:0xf bound_ctrl:1
	s_nop 0
	ds_write_b32 v3, v208 offset:62464
	v_add_f32_dpp v206, v206, v206 row_mirror row_mask:0xf bank_mask:0xf bound_ctrl:1
	s_waitcnt lgkmcnt(9)
	v_pk_fma_f32 v[114:115], v[104:105], v[206:207], v[164:165] op_sel_hi:[1,0,1] neg_lo:[1,0,0] neg_hi:[1,0,0]
	v_pk_fma_f32 v[112:113], v[106:107], v[206:207], v[170:171] op_sel_hi:[1,0,1] neg_lo:[1,0,0] neg_hi:[1,0,0]
	ds_read_b128 v[96:99], v204 offset:8960
	ds_read_b128 v[100:103], v204 offset:8976
	ds_read_b128 v[108:111], v204 offset:9008
	ds_read_b32 v168, v205 offset:20928
	ds_read_b128 v[104:107], v204 offset:8992
	s_waitcnt lgkmcnt(11)
	v_mul_f32_e32 v206, v76, v114
	v_mul_f32_e32 v208, v158, v114
	v_fmac_f32_e32 v206, v77, v115
	v_fmac_f32_e32 v208, v159, v115
	v_fmac_f32_e32 v206, v78, v112
	v_fmac_f32_e32 v208, v160, v112
	v_fmac_f32_e32 v206, v79, v113
	v_fmac_f32_e32 v208, v161, v113
	ds_read_b128 v[158:161], v204 offset:9024
	s_waitcnt lgkmcnt(11)
	v_pk_mul_f32 v[164:165], v[80:81], v[114:115]
	v_pk_mul_f32 v[170:171], v[82:83], v[112:113]
	v_add_f32_dpp v206, v206, v206 quad_perm:[1,0,3,2] row_mask:0xf bank_mask:0xf bound_ctrl:1
	v_add_f32_dpp v208, v208, v208 quad_perm:[1,0,3,2] row_mask:0xf bank_mask:0xf bound_ctrl:1
	s_waitcnt lgkmcnt(9)
	v_pk_fma_f32 v[164:165], v[88:89], v[166:167], v[164:165] op_sel_hi:[1,0,1]
	v_add_f32_dpp v206, v206, v206 quad_perm:[2,3,0,1] row_mask:0xf bank_mask:0xf bound_ctrl:1
	v_pk_fma_f32 v[170:171], v[90:91], v[166:167], v[170:171] op_sel_hi:[1,0,1]
	v_add_f32_dpp v208, v208, v208 quad_perm:[2,3,0,1] row_mask:0xf bank_mask:0xf bound_ctrl:1
	v_add_f32_dpp v206, v206, v206 row_half_mirror row_mask:0xf bank_mask:0xf bound_ctrl:1
	s_nop 0
	ds_write_b32 v3, v208 offset:62720
	v_add_f32_dpp v206, v206, v206 row_mirror row_mask:0xf bank_mask:0xf bound_ctrl:1
	s_waitcnt lgkmcnt(9)
; #define LAS __attribute__((address_space(3)))
; template <int CTRL> __device__ __forceinline__ float dppf(float x) { return __int_as_float(__builtin_amdgcn_mov_dpp(__float_as_int(x), CTRL, 0xF, 0xF, true)); }
; __device__ __forceinline__ void scan_phase(const Params& p, int layer, LAS unsigned char* lds, int tid) {
;     ...
;                 const LAS float* RW = inb; const LAS float* RV = inb + O_RV; LAS float* RO = outb;
;                 const LAS f32x4* q = (const LAS f32x4*)(RW + kq * 20);
;                 f32x4 kk = q[0], w = q[1], bb = q[2], k = q[3], r = q[4]; float v = RV[rrow];
; #pragma unroll
;                 for (int s = 0; s < 16; ++s) {
;                     f32x4 nkk = kk, nw = w, nbb = bb, nk = k, nr = r; float nv = v;
;                     if (s < 15) { const LAS f32x4* qn = (const LAS f32x4*)(RW + ((s + 1) * 16 + kq) * 20);
;                         nkk = qn[0]; nw = qn[1]; nbb = qn[2]; nk = qn[3]; nr = qn[4]; nv = RV[(s + 1) * 16 + rrow]; }
;                     const f32x2 p2 = S01 * kk.xy + S23 * kk.zw;
;                     float pd = p2.x + p2.y;
;                     const f32x2 a01 = S01 * w.xy + k.xy * v, a23 = S23 * w.zw + k.zw * v;
;                     pd = row16_sum(pd);
;                     S01 = a01 - bb.xy * pd; S23 = a23 - bb.zw * pd;
;                     const f32x2 o2 = S01 * r.xy + S23 * r.zw;
;                     float o = o2.x + o2.y;
;                     o += dppf<0xB1>(o); o += dppf<0x4E>(o);
;                     if ((kq & 3) == 0) RO[(s * 4 + (kq >> 2)) * 16 + rrow] = o;
;                     kk = nkk; w = nw; bb = nbb; k = nk; r = nr; v = nv;
;                 }
	v_pk_fma_f32 v[114:115], v[84:85], v[206:207], v[164:165] op_sel_hi:[1,0,1] neg_lo:[1,0,0] neg_hi:[1,0,0]
	v_pk_fma_f32 v[112:113], v[86:87], v[206:207], v[170:171] op_sel_hi:[1,0,1] neg_lo:[1,0,0] neg_hi:[1,0,0]
	ds_read_b128 v[76:79], v204 offset:10240
	ds_read_b128 v[80:83], v204 offset:10256
	ds_read_b128 v[88:91], v204 offset:10288
	ds_read_b32 v166, v205 offset:20992
	ds_read_b128 v[84:87], v204 offset:10272
	s_waitcnt lgkmcnt(11)
	v_mul_f32_e32 v206, v96, v114
	v_mul_f32_e32 v208, v92, v114
	v_fmac_f32_e32 v206, v97, v115
	v_fmac_f32_e32 v208, v93, v115
	v_fmac_f32_e32 v206, v98, v112
	v_fmac_f32_e32 v208, v94, v112
	v_fmac_f32_e32 v206, v99, v113
	v_fmac_f32_e32 v208, v95, v113
	ds_read_b128 v[92:95], v204 offset:10304
	s_waitcnt lgkmcnt(11)
	v_pk_mul_f32 v[164:165], v[100:101], v[114:115]
	v_pk_mul_f32 v[170:171], v[102:103], v[112:113]
	v_add_f32_dpp v206, v206, v206 quad_perm:[1,0,3,2] row_mask:0xf bank_mask:0xf bound_ctrl:1
	v_add_f32_dpp v208, v208, v208 quad_perm:[1,0,3,2] row_mask:0xf bank_mask:0xf bound_ctrl:1
	s_waitcnt lgkmcnt(9)
	v_pk_fma_f32 v[164:165], v[108:109], v[168:169], v[164:165] op_sel_hi:[1,0,1]
	v_add_f32_dpp v206, v206, v206 quad_perm:[2,3,0,1] row_mask:0xf bank_mask:0xf bound_ctrl:1
	v_pk_fma_f32 v[170:171], v[110:111], v[168:169], v[170:171] op_sel_hi:[1,0,1]
	v_add_f32_dpp v208, v208, v208 quad_perm:[2,3,0,1] row_mask:0xf bank_mask:0xf bound_ctrl:1
	v_add_f32_dpp v206, v206, v206 row_half_mirror row_mask:0xf bank_mask:0xf bound_ctrl:1
	s_nop 0
	ds_write_b32 v3, v208 offset:62976
	v_add_f32_dpp v206, v206, v206 row_mirror row_mask:0xf bank_mask:0xf bound_ctrl:1
	s_waitcnt lgkmcnt(9)
	v_pk_fma_f32 v[114:115], v[104:105], v[206:207], v[164:165] op_sel_hi:[1,0,1] neg_lo:[1,0,0] neg_hi:[1,0,0]
	v_pk_fma_f32 v[112:113], v[106:107], v[206:207], v[170:171] op_sel_hi:[1,0,1] neg_lo:[1,0,0] neg_hi:[1,0,0]
	ds_read_b128 v[96:99], v204 offset:11520
	ds_read_b128 v[100:103], v204 offset:11536
	ds_read_b128 v[108:111], v204 offset:11568
	ds_read_b32 v168, v205 offset:21056
	ds_read_b128 v[104:107], v204 offset:11552
	s_waitcnt lgkmcnt(11)
	v_mul_f32_e32 v206, v76, v114
	v_mul_f32_e32 v208, v158, v114
	v_fmac_f32_e32 v206, v77, v115
	v_fmac_f32_e32 v208, v159, v115
	v_fmac_f32_e32 v206, v78, v112
	v_fmac_f32_e32 v208, v160, v112
	v_fmac_f32_e32 v206, v79, v113
	v_fmac_f32_e32 v208, v161, v113
	ds_read_b128 v[158:161], v204 offset:11584
	s_waitcnt lgkmcnt(11)
	v_pk_mul_f32 v[164:165], v[80:81], v[114:115]
	v_pk_mul_f32 v[170:171], v[82:83], v[112:113]
	v_add_f32_dpp v206, v206, v206 quad_perm:[1,0,3,2] row_mask:0xf bank_mask:0xf bound_ctrl:1
	v_add_f32_dpp v208, v208, v208 quad_perm:[1,0,3,2] row_mask:0xf bank_mask:0xf bound_ctrl:1
	s_waitcnt lgkmcnt(9)
	v_pk_fma_f32 v[164:165], v[88:89], v[166:167], v[164:165] op_sel_hi:[1,0,1]
	v_add_f32_dpp v206, v206, v206 quad_perm:[2,3,0,1] row_mask:0xf bank_mask:0xf bound_ctrl:1
	v_pk_fma_f32 v[170:171], v[90:91], v[166:167], v[170:171] op_sel_hi:[1,0,1]
	v_add_f32_dpp v208, v208, v208 quad_perm:[2,3,0,1] row_mask:0xf bank_mask:0xf bound_ctrl:1
	v_add_f32_dpp v206, v206, v206 row_half_mirror row_mask:0xf bank_mask:0xf bound_ctrl:1
	s_nop 0
	ds_write_b32 v3, v208 offset:63232
	v_add_f32_dpp v206, v206, v206 row_mirror row_mask:0xf bank_mask:0xf bound_ctrl:1
	s_waitcnt lgkmcnt(9)
	v_pk_fma_f32 v[114:115], v[84:85], v[206:207], v[164:165] op_sel_hi:[1,0,1] neg_lo:[1,0,0] neg_hi:[1,0,0]
	v_pk_fma_f32 v[112:113], v[86:87], v[206:207], v[170:171] op_sel_hi:[1,0,1] neg_lo:[1,0,0] neg_hi:[1,0,0]
	ds_read_b128 v[76:79], v204 offset:12800
	ds_read_b128 v[80:83], v204 offset:12816
	ds_read_b128 v[88:91], v204 offset:12848
	ds_read_b32 v166, v205 offset:21120
	ds_read_b128 v[84:87], v204 offset:12832
	s_waitcnt lgkmcnt(11)
	v_mul_f32_e32 v206, v96, v114
	v_mul_f32_e32 v208, v92, v114
	v_fmac_f32_e32 v206, v97, v115
	v_fmac_f32_e32 v208, v93, v115
	v_fmac_f32_e32 v206, v98, v112
	v_fmac_f32_e32 v208, v94, v112
	v_fmac_f32_e32 v206, v99, v113
	v_fmac_f32_e32 v208, v95, v113
	ds_read_b128 v[92:95], v204 offset:12864
	s_waitcnt lgkmcnt(11)
	v_pk_mul_f32 v[164:165], v[100:101], v[114:115]
	v_pk_mul_f32 v[170:171], v[102:103], v[112:113]
	v_add_f32_dpp v206, v206, v206 quad_perm:[1,0,3,2] row_mask:0xf bank_mask:0xf bound_ctrl:1
	v_add_f32_dpp v208, v208, v208 quad_perm:[1,0,3,2] row_mask:0xf bank_mask:0xf bound_ctrl:1
	s_waitcnt lgkmcnt(9)
	v_pk_fma_f32 v[164:165], v[108:109], v[168:169], v[164:165] op_sel_hi:[1,0,1]
	v_add_f32_dpp v206, v206, v206 quad_perm:[2,3,0,1] row_mask:0xf bank_mask:0xf bound_ctrl:1
	v_pk_fma_f32 v[170:171], v[110:111], v[168:169], v[170:171] op_sel_hi:[1,0,1]
	v_add_f32_dpp v208, v208, v208 quad_perm:[2,3,0,1] row_mask:0xf bank_mask:0xf bound_ctrl:1
	v_add_f32_dpp v206, v206, v206 row_half_mirror row_mask:0xf bank_mask:0xf bound_ctrl:1
	s_nop 0
	ds_write_b32 v3, v208 offset:63488
	v_add_f32_dpp v206, v206, v206 row_mirror row_mask:0xf bank_mask:0xf bound_ctrl:1
	s_waitcnt lgkmcnt(9)
	v_pk_fma_f32 v[114:115], v[104:105], v[206:207], v[164:165] op_sel_hi:[1,0,1] neg_lo:[1,0,0] neg_hi:[1,0,0]
	v_pk_fma_f32 v[112:113], v[106:107], v[206:207], v[170:171] op_sel_hi:[1,0,1] neg_lo:[1,0,0] neg_hi:[1,0,0]
	ds_read_b128 v[96:99], v204 offset:14080
	ds_read_b128 v[100:103], v204 offset:14096
	ds_read_b128 v[108:111], v204 offset:14128
	ds_read_b32 v168, v205 offset:21184
	ds_read_b128 v[104:107], v204 offset:14112
	s_waitcnt lgkmcnt(11)
	v_mul_f32_e32 v206, v76, v114
	v_mul_f32_e32 v208, v158, v114
	v_fmac_f32_e32 v206, v77, v115
	v_fmac_f32_e32 v208, v159, v115
	v_fmac_f32_e32 v206, v78, v112
	v_fmac_f32_e32 v208, v160, v112
	v_fmac_f32_e32 v206, v79, v113
	v_fmac_f32_e32 v208, v161, v113
	ds_read_b128 v[158:161], v204 offset:14144
	s_waitcnt lgkmcnt(11)
; #define LAS __attribute__((address_space(3)))
; template <int CTRL> __device__ __forceinline__ float dppf(float x) { return __int_as_float(__builtin_amdgcn_mov_dpp(__float_as_int(x), CTRL, 0xF, 0xF, true)); }
; __device__ __forceinline__ void scan_phase(const Params& p, int layer, LAS unsigned char* lds, int tid) {
;     ...
;                 const LAS float* RW = inb; const LAS float* RV = inb + O_RV; LAS float* RO = outb;
;                 const LAS f32x4* q = (const LAS f32x4*)(RW + kq * 20);
;                 f32x4 kk = q[0], w = q[1], bb = q[2], k = q[3], r = q[4]; float v = RV[rrow];
; #pragma unroll
;                 for (int s = 0; s < 16; ++s) {
;                     f32x4 nkk = kk, nw = w, nbb = bb, nk = k, nr = r; float nv = v;
;                     if (s < 15) { const LAS f32x4* qn = (const LAS f32x4*)(RW + ((s + 1) * 16 + kq) * 20);
;                         nkk = qn[0]; nw = qn[1]; nbb = qn[2]; nk = qn[3]; nr = qn[4]; nv = RV[(s + 1) * 16 + rrow]; }
;                     const f32x2 p2 = S01 * kk.xy + S23 * kk.zw;
;                     float pd = p2.x + p2.y;
;                     const f32x2 a01 = S01 * w.xy + k.xy * v, a23 = S23 * w.zw + k.zw * v;
;                     pd = row16_sum(pd);
;                     S01 = a01 - bb.xy * pd; S23 = a23 - bb.zw * pd;
;                     const f32x2 o2 = S01 * r.xy + S23 * r.zw;
;                     float o = o2.x + o2.y;
;                     o += dppf<0xB1>(o); o += dppf<0x4E>(o);
;                     if ((kq & 3) == 0) RO[(s * 4 + (kq >> 2)) * 16 + rrow] = o;
;                     kk = nkk; w = nw; bb = nbb; k = nk; r = nr; v = nv;
;                 }
	v_pk_mul_f32 v[164:165], v[80:81], v[114:115]
	v_pk_mul_f32 v[170:171], v[82:83], v[112:113]
	v_add_f32_dpp v206, v206, v206 quad_perm:[1,0,3,2] row_mask:0xf bank_mask:0xf bound_ctrl:1
	v_add_f32_dpp v208, v208, v208 quad_perm:[1,0,3,2] row_mask:0xf bank_mask:0xf bound_ctrl:1
	s_waitcnt lgkmcnt(9)
	v_pk_fma_f32 v[164:165], v[88:89], v[166:167], v[164:165] op_sel_hi:[1,0,1]
	v_add_f32_dpp v206, v206, v206 quad_perm:[2,3,0,1] row_mask:0xf bank_mask:0xf bound_ctrl:1
	v_pk_fma_f32 v[170:171], v[90:91], v[166:167], v[170:171] op_sel_hi:[1,0,1]
	v_add_f32_dpp v208, v208, v208 quad_perm:[2,3,0,1] row_mask:0xf bank_mask:0xf bound_ctrl:1
	v_add_f32_dpp v206, v206, v206 row_half_mirror row_mask:0xf bank_mask:0xf bound_ctrl:1
	s_nop 0
	ds_write_b32 v3, v208 offset:63744
	v_add_f32_dpp v206, v206, v206 row_mirror row_mask:0xf bank_mask:0xf bound_ctrl:1
	s_waitcnt lgkmcnt(9)
	v_pk_fma_f32 v[114:115], v[84:85], v[206:207], v[164:165] op_sel_hi:[1,0,1] neg_lo:[1,0,0] neg_hi:[1,0,0]
	v_pk_fma_f32 v[112:113], v[86:87], v[206:207], v[170:171] op_sel_hi:[1,0,1] neg_lo:[1,0,0] neg_hi:[1,0,0]
	ds_read_b128 v[76:79], v204 offset:15360
	ds_read_b128 v[80:83], v204 offset:15376
	ds_read_b128 v[88:91], v204 offset:15408
	ds_read_b32 v166, v205 offset:21248
	ds_read_b128 v[84:87], v204 offset:15392
	s_waitcnt lgkmcnt(11)
	v_mul_f32_e32 v206, v96, v114
	v_mul_f32_e32 v208, v92, v114
	v_fmac_f32_e32 v206, v97, v115
	v_fmac_f32_e32 v208, v93, v115
	v_fmac_f32_e32 v206, v98, v112
	v_fmac_f32_e32 v208, v94, v112
	v_fmac_f32_e32 v206, v99, v113
	v_fmac_f32_e32 v208, v95, v113
	ds_read_b128 v[92:95], v204 offset:15424
	s_waitcnt lgkmcnt(11)
	v_pk_mul_f32 v[164:165], v[100:101], v[114:115]
	v_pk_mul_f32 v[170:171], v[102:103], v[112:113]
	v_add_f32_dpp v206, v206, v206 quad_perm:[1,0,3,2] row_mask:0xf bank_mask:0xf bound_ctrl:1
	v_add_f32_dpp v208, v208, v208 quad_perm:[1,0,3,2] row_mask:0xf bank_mask:0xf bound_ctrl:1
	s_waitcnt lgkmcnt(9)
	v_pk_fma_f32 v[164:165], v[108:109], v[168:169], v[164:165] op_sel_hi:[1,0,1]
	v_add_f32_dpp v206, v206, v206 quad_perm:[2,3,0,1] row_mask:0xf bank_mask:0xf bound_ctrl:1
	v_pk_fma_f32 v[170:171], v[110:111], v[168:169], v[170:171] op_sel_hi:[1,0,1]
	v_add_f32_dpp v208, v208, v208 quad_perm:[2,3,0,1] row_mask:0xf bank_mask:0xf bound_ctrl:1
	v_add_f32_dpp v206, v206, v206 row_half_mirror row_mask:0xf bank_mask:0xf bound_ctrl:1
	s_nop 0
	ds_write_b32 v3, v208 offset:64000
	v_add_f32_dpp v206, v206, v206 row_mirror row_mask:0xf bank_mask:0xf bound_ctrl:1
	s_waitcnt lgkmcnt(9)
	v_pk_fma_f32 v[114:115], v[104:105], v[206:207], v[164:165] op_sel_hi:[1,0,1] neg_lo:[1,0,0] neg_hi:[1,0,0]
	v_pk_fma_f32 v[112:113], v[106:107], v[206:207], v[170:171] op_sel_hi:[1,0,1] neg_lo:[1,0,0] neg_hi:[1,0,0]
	ds_read_b128 v[96:99], v204 offset:16640
	ds_read_b128 v[100:103], v204 offset:16656
	ds_read_b128 v[108:111], v204 offset:16688
	ds_read_b32 v168, v205 offset:21312
	ds_read_b128 v[104:107], v204 offset:16672
	s_waitcnt lgkmcnt(11)
	v_mul_f32_e32 v206, v76, v114
	v_mul_f32_e32 v208, v158, v114
	v_fmac_f32_e32 v206, v77, v115
	v_fmac_f32_e32 v208, v159, v115
	v_fmac_f32_e32 v206, v78, v112
	v_fmac_f32_e32 v208, v160, v112
	v_fmac_f32_e32 v206, v79, v113
	v_fmac_f32_e32 v208, v161, v113
	ds_read_b128 v[158:161], v204 offset:16704
	s_waitcnt lgkmcnt(11)
	v_pk_mul_f32 v[164:165], v[80:81], v[114:115]
	v_pk_mul_f32 v[170:171], v[82:83], v[112:113]
	v_add_f32_dpp v206, v206, v206 quad_perm:[1,0,3,2] row_mask:0xf bank_mask:0xf bound_ctrl:1
	v_add_f32_dpp v208, v208, v208 quad_perm:[1,0,3,2] row_mask:0xf bank_mask:0xf bound_ctrl:1
	s_waitcnt lgkmcnt(9)
	v_pk_fma_f32 v[164:165], v[88:89], v[166:167], v[164:165] op_sel_hi:[1,0,1]
	v_add_f32_dpp v206, v206, v206 quad_perm:[2,3,0,1] row_mask:0xf bank_mask:0xf bound_ctrl:1
	v_pk_fma_f32 v[170:171], v[90:91], v[166:167], v[170:171] op_sel_hi:[1,0,1]
	v_add_f32_dpp v208, v208, v208 quad_perm:[2,3,0,1] row_mask:0xf bank_mask:0xf bound_ctrl:1
	v_add_f32_dpp v206, v206, v206 row_half_mirror row_mask:0xf bank_mask:0xf bound_ctrl:1
	s_nop 0
	ds_write_b32 v3, v208 offset:64256
	v_add_f32_dpp v206, v206, v206 row_mirror row_mask:0xf bank_mask:0xf bound_ctrl:1
	s_waitcnt lgkmcnt(9)
	v_pk_fma_f32 v[114:115], v[84:85], v[206:207], v[164:165] op_sel_hi:[1,0,1] neg_lo:[1,0,0] neg_hi:[1,0,0]
	v_pk_fma_f32 v[112:113], v[86:87], v[206:207], v[170:171] op_sel_hi:[1,0,1] neg_lo:[1,0,0] neg_hi:[1,0,0]
	ds_read_b128 v[76:79], v204 offset:17920
	ds_read_b128 v[80:83], v204 offset:17936
	ds_read_b128 v[88:91], v204 offset:17968
	ds_read_b32 v166, v205 offset:21376
	ds_read_b128 v[84:87], v204 offset:17952
	s_waitcnt lgkmcnt(11)
	v_mul_f32_e32 v206, v96, v114
	v_mul_f32_e32 v208, v92, v114
	v_fmac_f32_e32 v206, v97, v115
	v_fmac_f32_e32 v208, v93, v115
	v_fmac_f32_e32 v206, v98, v112
	v_fmac_f32_e32 v208, v94, v112
	v_fmac_f32_e32 v206, v99, v113
	v_fmac_f32_e32 v208, v95, v113
	ds_read_b128 v[92:95], v204 offset:17984
	s_waitcnt lgkmcnt(11)
; #define LAS __attribute__((address_space(3)))
; template <int CTRL> __device__ __forceinline__ float dppf(float x) { return __int_as_float(__builtin_amdgcn_mov_dpp(__float_as_int(x), CTRL, 0xF, 0xF, true)); }
; __device__ __forceinline__ void scan_phase(const Params& p, int layer, LAS unsigned char* lds, int tid) {
;     ...
;                 const LAS float* RW = inb; const LAS float* RV = inb + O_RV; LAS float* RO = outb;
;                 const LAS f32x4* q = (const LAS f32x4*)(RW + kq * 20);
;                 f32x4 kk = q[0], w = q[1], bb = q[2], k = q[3], r = q[4]; float v = RV[rrow];
; #pragma unroll
;                 for (int s = 0; s < 16; ++s) {
;                     f32x4 nkk = kk, nw = w, nbb = bb, nk = k, nr = r; float nv = v;
;                     if (s < 15) { const LAS f32x4* qn = (const LAS f32x4*)(RW + ((s + 1) * 16 + kq) * 20);
;                         nkk = qn[0]; nw = qn[1]; nbb = qn[2]; nk = qn[3]; nr = qn[4]; nv = RV[(s + 1) * 16 + rrow]; }
;                     const f32x2 p2 = S01 * kk.xy + S23 * kk.zw;
;                     float pd = p2.x + p2.y;
;                     const f32x2 a01 = S01 * w.xy + k.xy * v, a23 = S23 * w.zw + k.zw * v;
;                     pd = row16_sum(pd);
;                     S01 = a01 - bb.xy * pd; S23 = a23 - bb.zw * pd;
;                     const f32x2 o2 = S01 * r.xy + S23 * r.zw;
;                     float o = o2.x + o2.y;
;                     o += dppf<0xB1>(o); o += dppf<0x4E>(o);
;                     if ((kq & 3) == 0) RO[(s * 4 + (kq >> 2)) * 16 + rrow] = o;
;                     kk = nkk; w = nw; bb = nbb; k = nk; r = nr; v = nv;
;                 }
	v_pk_mul_f32 v[164:165], v[100:101], v[114:115]
	v_pk_mul_f32 v[170:171], v[102:103], v[112:113]
	v_add_f32_dpp v206, v206, v206 quad_perm:[1,0,3,2] row_mask:0xf bank_mask:0xf bound_ctrl:1
	v_add_f32_dpp v208, v208, v208 quad_perm:[1,0,3,2] row_mask:0xf bank_mask:0xf bound_ctrl:1
	s_waitcnt lgkmcnt(9)
	v_pk_fma_f32 v[164:165], v[108:109], v[168:169], v[164:165] op_sel_hi:[1,0,1]
	v_add_f32_dpp v206, v206, v206 quad_perm:[2,3,0,1] row_mask:0xf bank_mask:0xf bound_ctrl:1
	v_pk_fma_f32 v[170:171], v[110:111], v[168:169], v[170:171] op_sel_hi:[1,0,1]
	v_add_f32_dpp v208, v208, v208 quad_perm:[2,3,0,1] row_mask:0xf bank_mask:0xf bound_ctrl:1
	v_add_f32_dpp v206, v206, v206 row_half_mirror row_mask:0xf bank_mask:0xf bound_ctrl:1
	s_nop 0
	ds_write_b32 v3, v208 offset:64512
	v_add_f32_dpp v206, v206, v206 row_mirror row_mask:0xf bank_mask:0xf bound_ctrl:1
	s_waitcnt lgkmcnt(9)
	v_pk_fma_f32 v[114:115], v[104:105], v[206:207], v[164:165] op_sel_hi:[1,0,1] neg_lo:[1,0,0] neg_hi:[1,0,0]
	v_pk_fma_f32 v[112:113], v[106:107], v[206:207], v[170:171] op_sel_hi:[1,0,1] neg_lo:[1,0,0] neg_hi:[1,0,0]
	ds_read_b128 v[96:99], v204 offset:19200
	ds_read_b128 v[100:103], v204 offset:19216
	ds_read_b128 v[108:111], v204 offset:19248
	ds_read_b32 v168, v205 offset:21440
	ds_read_b128 v[104:107], v204 offset:19232
	s_waitcnt lgkmcnt(11)
	v_mul_f32_e32 v206, v76, v114
	v_mul_f32_e32 v208, v158, v114
	v_fmac_f32_e32 v206, v77, v115
	v_fmac_f32_e32 v208, v159, v115
	v_fmac_f32_e32 v206, v78, v112
	v_fmac_f32_e32 v208, v160, v112
	v_fmac_f32_e32 v206, v79, v113
	v_fmac_f32_e32 v208, v161, v113
	ds_read_b128 v[158:161], v204 offset:19264
	s_waitcnt lgkmcnt(11)
	v_pk_mul_f32 v[164:165], v[80:81], v[114:115]
	v_pk_mul_f32 v[170:171], v[82:83], v[112:113]
	v_add_f32_dpp v206, v206, v206 quad_perm:[1,0,3,2] row_mask:0xf bank_mask:0xf bound_ctrl:1
	v_add_f32_dpp v208, v208, v208 quad_perm:[1,0,3,2] row_mask:0xf bank_mask:0xf bound_ctrl:1
	s_waitcnt lgkmcnt(9)
	v_pk_fma_f32 v[164:165], v[88:89], v[166:167], v[164:165] op_sel_hi:[1,0,1]
	v_add_f32_dpp v206, v206, v206 quad_perm:[2,3,0,1] row_mask:0xf bank_mask:0xf bound_ctrl:1
	v_pk_fma_f32 v[170:171], v[90:91], v[166:167], v[170:171] op_sel_hi:[1,0,1]
	v_add_f32_dpp v208, v208, v208 quad_perm:[2,3,0,1] row_mask:0xf bank_mask:0xf bound_ctrl:1
	v_add_f32_dpp v206, v206, v206 row_half_mirror row_mask:0xf bank_mask:0xf bound_ctrl:1
	s_nop 0
	ds_write_b32 v3, v208 offset:64768
	v_add_f32_dpp v206, v206, v206 row_mirror row_mask:0xf bank_mask:0xf bound_ctrl:1
	s_waitcnt lgkmcnt(9)
	v_pk_fma_f32 v[114:115], v[84:85], v[206:207], v[164:165] op_sel_hi:[1,0,1] neg_lo:[1,0,0] neg_hi:[1,0,0]
	v_pk_fma_f32 v[112:113], v[86:87], v[206:207], v[170:171] op_sel_hi:[1,0,1] neg_lo:[1,0,0] neg_hi:[1,0,0]
	s_waitcnt lgkmcnt(6)
	v_mul_f32_e32 v206, v96, v114
	v_mul_f32_e32 v208, v92, v114
	v_fmac_f32_e32 v206, v97, v115
	v_fmac_f32_e32 v208, v93, v115
	v_fmac_f32_e32 v206, v98, v112
	v_fmac_f32_e32 v208, v94, v112
	v_fmac_f32_e32 v206, v99, v113
	v_fmac_f32_e32 v208, v95, v113
	s_waitcnt lgkmcnt(5)
	v_pk_mul_f32 v[164:165], v[100:101], v[114:115]
	v_pk_mul_f32 v[170:171], v[102:103], v[112:113]
	v_add_f32_dpp v206, v206, v206 quad_perm:[1,0,3,2] row_mask:0xf bank_mask:0xf bound_ctrl:1
	v_add_f32_dpp v208, v208, v208 quad_perm:[1,0,3,2] row_mask:0xf bank_mask:0xf bound_ctrl:1
	s_waitcnt lgkmcnt(3)
	v_pk_fma_f32 v[164:165], v[108:109], v[168:169], v[164:165] op_sel_hi:[1,0,1]
	v_add_f32_dpp v206, v206, v206 quad_perm:[2,3,0,1] row_mask:0xf bank_mask:0xf bound_ctrl:1
	v_pk_fma_f32 v[170:171], v[110:111], v[168:169], v[170:171] op_sel_hi:[1,0,1]
	v_add_f32_dpp v208, v208, v208 quad_perm:[2,3,0,1] row_mask:0xf bank_mask:0xf bound_ctrl:1
	v_add_f32_dpp v206, v206, v206 row_half_mirror row_mask:0xf bank_mask:0xf bound_ctrl:1
	s_nop 0
	ds_write_b32 v3, v208 offset:65024
	v_add_f32_dpp v206, v206, v206 row_mirror row_mask:0xf bank_mask:0xf bound_ctrl:1
	s_waitcnt lgkmcnt(3)
	v_pk_fma_f32 v[114:115], v[104:105], v[206:207], v[164:165] op_sel_hi:[1,0,1] neg_lo:[1,0,0] neg_hi:[1,0,0]
	v_pk_fma_f32 v[112:113], v[106:107], v[206:207], v[170:171] op_sel_hi:[1,0,1] neg_lo:[1,0,0] neg_hi:[1,0,0]
	s_nop 0
	s_waitcnt lgkmcnt(2)
	v_mul_f32_e32 v208, v158, v114
	v_fmac_f32_e32 v208, v159, v115
	v_fmac_f32_e32 v208, v160, v112
	v_fmac_f32_e32 v208, v161, v113
	s_nop 1
	v_add_f32_dpp v208, v208, v208 quad_perm:[1,0,3,2] row_mask:0xf bank_mask:0xf bound_ctrl:1
	s_nop 1
	v_add_f32_dpp v208, v208, v208 quad_perm:[2,3,0,1] row_mask:0xf bank_mask:0xf bound_ctrl:1
	ds_write_b32 v3, v208 offset:65280
	s_branch .LBB0_280
.LBB0_453:
	s_or_b64 exec, exec, s[10:11]
	s_branch .Lscan_wo
